# speedup vs baseline: 1.0009x; 1.0009x over previous
; template <int MODE>
; __device__ __forceinline__ void gemm_tile(const int ph, const int which, const int pm, const int pn) {
;     ...
;   if (MODE == 3) {
;     unsigned char* Gs = smem;
;     float rsv[2][4];
;     float4 w0[2], w1[2], w2[2], bb[2];
; #pragma unroll
;     for (int n = 0; n < 2; ++n) {
;       const int j = ecol + wc * 32 + n * 16 + fq * 4;
;       w0[n] = *(const float4*)(cw + j);
;       w1[n] = *(const float4*)(cw + DFF + j);
;       w2[n] = *(const float4*)(cw + 2 * DFF + j);
;       bb[n] = *(const float4*)(cb + j);
;     }
; #pragma unroll
;     for (int ai = 0; ai < 2; ++ai)
; #pragma unroll
;       for (int m = 0; m < 4; ++m) {
;         const int lr = ai * HALF + wr * 64 + m * 16 + fr;
;         const int gr = browC + lr;
;         const float s = scale[gr];
;         rsv[ai][m] = s;
; #pragma unroll
;         for (int n = 0; n < 2; ++n) {
;           const int c = wc * 32 + n * 16 + fq * 4;
;           f32x4 v = acc[ai][0][m][n];
;           uint2 o;
;           o.x = pack2(v[0] * s, v[1] * s);
;           o.y = pack2(v[2] * s, v[3] * s);
;           *(uint2*)(Gs + lr * 264 + c * 2) = o;
;         }
;       }
;     __syncthreads();
.LBB0_403:
	v_bfe_u32 v244, v208, 4, 1
	v_mul_u32_u24_e32 v244, 24, v244
	v_add_u32_e32 v164, s26, v163
	v_ashrrev_i32_e32 v165, 31, v164
	v_lshlrev_b32_e32 v28, 2, v162
	v_lshl_add_u64 v[26:27], v[164:165], 2, s[18:19]
	s_add_u32 s4, s2, 0x2c00
	s_movk_i32 s5, 0x108
	v_lshl_or_b32 v165, v0, 5, v28
	global_load_dword v194, v[26:27], off
	global_load_dword v184, v[26:27], off offset:64
	global_load_dword v174, v[26:27], off offset:128
	global_load_dword v172, v[26:27], off offset:192
	global_load_dword v170, v[26:27], off offset:512
	v_lshlrev_b32_e32 v29, 3, v162
	v_mul_lo_u32 v185, v163, s5
	s_addc_u32 s5, s3, 0
	v_or_b32_e32 v28, s6, v165
	v_lshl_or_b32 v0, v0, 6, v29
	global_load_dword v168, v[26:27], off offset:576
	global_load_dword v166, v[26:27], off offset:640
	global_load_dword v162, v[26:27], off offset:704
	s_add_u32 s16, s2, 0x5800
	v_ashrrev_i32_e32 v29, 31, v28
	v_or_b32_e32 v30, 16, v28
	s_addc_u32 s17, s3, 0
	v_lshlrev_b64 v[26:27], 2, v[28:29]
	v_ashrrev_i32_e32 v31, 31, v30
	v_lshl_add_u64 v[28:29], s[2:3], 0, v[26:27]
	v_lshl_add_u64 v[32:33], s[4:5], 0, v[26:27]
	v_lshl_add_u64 v[34:35], s[16:17], 0, v[26:27]
	v_lshl_add_u64 v[36:37], s[8:9], 0, v[26:27]
	v_lshlrev_b64 v[26:27], 2, v[30:31]
	v_lshl_add_u64 v[38:39], s[4:5], 0, v[26:27]
	v_lshl_add_u64 v[176:177], s[16:17], 0, v[26:27]
	global_load_dwordx4 v[42:45], v[32:33], off
	global_load_dwordx4 v[46:49], v[34:35], off
	global_load_dwordx4 v[50:53], v[28:29], off
	s_nop 0
	global_load_dwordx4 v[26:29], v[28:29], off offset:64
	s_nop 0
	global_load_dwordx4 v[54:57], v[36:37], off
	global_load_dwordx4 v[30:33], v[36:37], off offset:64
	s_nop 0
	global_load_dwordx4 v[38:41], v[38:39], off
	s_nop 0
	global_load_dwordx4 v[34:37], v[176:177], off
	v_add_u32_e32 v175, 0x1080, v185
	v_add_u32_e32 v173, 0x2100, v185
	v_add_u32_e32 v195, v0, v185
	v_add_u32_e32 v171, 0x3180, v185
	v_add_u32_e32 v169, 0x8400, v185
	v_add_u32_e32 v210, v0, v175
	v_add_u32_e32 v211, v0, v173
	v_add_u32_e32 v212, v0, v171
	v_add_u32_e32 v213, v0, v169
	v_cmp_gt_i32_e32 vcc, s36, v164
	s_ashr_i32 s7, s6, 31
	s_lshl_b64 s[2:3], s[6:7], 1
	s_add_u32 s2, s10, s2
	s_addc_u32 s3, s11, s3
	s_waitcnt vmcnt(15)
	v_pk_mul_f32 v[206:207], v[106:107], v[194:195] op_sel_hi:[1,0]
	v_pk_mul_f32 v[204:205], v[108:109], v[194:195] op_sel_hi:[1,0]
	v_pk_mul_f32 v[202:203], v[110:111], v[194:195] op_sel_hi:[1,0]
	v_pk_mul_f32 v[200:201], v[112:113], v[194:195] op_sel_hi:[1,0]
	s_waitcnt vmcnt(13)
	v_pk_mul_f32 v[182:183], v[126:127], v[174:175] op_sel_hi:[1,0]
	v_pk_mul_f32 v[180:181], v[128:129], v[174:175] op_sel_hi:[1,0]
	s_waitcnt vmcnt(12)
	v_pk_mul_f32 v[178:179], v[130:131], v[172:173] op_sel_hi:[1,0]
	v_pk_mul_f32 v[176:177], v[132:133], v[172:173] op_sel_hi:[1,0]
	v_pk_mul_f32 v[134:135], v[134:135], v[172:173] op_sel_hi:[1,0]
	v_pk_mul_f32 v[132:133], v[136:137], v[172:173] op_sel_hi:[1,0]
	v_pk_mul_f32 v[198:199], v[114:115], v[184:185] op_sel_hi:[1,0]
	v_pk_mul_f32 v[196:197], v[116:117], v[184:185] op_sel_hi:[1,0]
	v_pk_mul_f32 v[192:193], v[118:119], v[184:185] op_sel_hi:[1,0]
	v_pk_mul_f32 v[190:191], v[120:121], v[184:185] op_sel_hi:[1,0]
	v_pk_mul_f32 v[188:189], v[122:123], v[174:175] op_sel_hi:[1,0]
	v_pk_mul_f32 v[186:187], v[124:125], v[174:175] op_sel_hi:[1,0]
	s_waitcnt vmcnt(11)
	v_pk_mul_f32 v[130:131], v[158:159], v[170:171] op_sel_hi:[1,0]
	v_cvt_pk_bf16_f32 v106, v206, v207
	v_cvt_pk_bf16_f32 v107, v204, v205
	v_cvt_pk_bf16_f32 v108, v202, v203
	v_cvt_pk_bf16_f32 v109, v200, v201
	v_cvt_pk_bf16_f32 v116, v182, v183
	v_cvt_pk_bf16_f32 v117, v180, v181
	v_cvt_pk_bf16_f32 v118, v178, v179
	v_cvt_pk_bf16_f32 v119, v176, v177
	v_cvt_pk_bf16_f32 v120, v134, v135
	v_cvt_pk_bf16_f32 v121, v132, v133
	v_pk_mul_f32 v[128:129], v[160:161], v[170:171] op_sel_hi:[1,0]
	v_pk_mul_f32 v[126:127], v[154:155], v[170:171] op_sel_hi:[1,0]
	v_pk_mul_f32 v[124:125], v[156:157], v[170:171] op_sel_hi:[1,0]
	v_cvt_pk_bf16_f32 v110, v198, v199
	v_cvt_pk_bf16_f32 v111, v196, v197
	v_cvt_pk_bf16_f32 v112, v192, v193
	v_cvt_pk_bf16_f32 v113, v190, v191
	v_cvt_pk_bf16_f32 v114, v188, v189
	v_cvt_pk_bf16_f32 v115, v186, v187
	ds_write2_b64 v195, v[106:107], v[108:109] offset1:4
	ds_write2_b64 v210, v[110:111], v[112:113] offset1:4
	ds_write2_b64 v211, v[114:115], v[116:117] offset1:4
	ds_write2_b64 v212, v[118:119], v[120:121] offset1:4
	v_cvt_pk_bf16_f32 v106, v130, v131
	v_cvt_pk_bf16_f32 v107, v128, v129
	v_cvt_pk_bf16_f32 v108, v126, v127
	v_cvt_pk_bf16_f32 v109, v124, v125
	v_add_u32_e32 v154, 0x9480, v185
	s_waitcnt vmcnt(10)
	v_pk_mul_f32 v[122:123], v[150:151], v[168:169] op_sel_hi:[1,0]
	v_pk_mul_f32 v[120:121], v[152:153], v[168:169] op_sel_hi:[1,0]
	v_pk_mul_f32 v[118:119], v[146:147], v[168:169] op_sel_hi:[1,0]
	v_pk_mul_f32 v[116:117], v[148:149], v[168:169] op_sel_hi:[1,0]
	ds_write2_b64 v213, v[106:107], v[108:109] offset1:4
	v_add_u32_e32 v110, v0, v154
	v_cvt_pk_bf16_f32 v106, v122, v123
	v_cvt_pk_bf16_f32 v107, v120, v121
	v_cvt_pk_bf16_f32 v108, v118, v119
	v_cvt_pk_bf16_f32 v109, v116, v117
	ds_write2_b64 v110, v[106:107], v[108:109] offset1:4
	v_add_u32_e32 v146, 0xa500, v185
	s_waitcnt vmcnt(9)
	v_pk_mul_f32 v[114:115], v[142:143], v[166:167] op_sel_hi:[1,0]
	v_pk_mul_f32 v[112:113], v[144:145], v[166:167] op_sel_hi:[1,0]
	v_pk_mul_f32 v[110:111], v[138:139], v[166:167] op_sel_hi:[1,0]
	v_pk_mul_f32 v[108:109], v[140:141], v[166:167] op_sel_hi:[1,0]
	v_add_u32_e32 v147, v0, v146
	v_cvt_pk_bf16_f32 v106, v114, v115
	v_cvt_pk_bf16_f32 v107, v112, v113
	v_cvt_pk_bf16_f32 v136, v110, v111
	v_cvt_pk_bf16_f32 v137, v108, v109
	ds_write2_b64 v147, v[106:107], v[136:137] offset1:4
	v_add_u32_e32 v138, 0xb580, v185
	s_waitcnt vmcnt(8)
	v_pk_mul_f32 v[106:107], v[102:103], v[162:163] op_sel_hi:[1,0]
	v_pk_mul_f32 v[104:105], v[104:105], v[162:163] op_sel_hi:[1,0]
	v_pk_mul_f32 v[102:103], v[98:99], v[162:163] op_sel_hi:[1,0]
	v_pk_mul_f32 v[98:99], v[100:101], v[162:163] op_sel_hi:[1,0]
	v_add_u32_e32 v0, v0, v138
	v_cvt_pk_bf16_f32 v136, v106, v107
	v_cvt_pk_bf16_f32 v137, v104, v105
	v_cvt_pk_bf16_f32 v140, v102, v103
	v_cvt_pk_bf16_f32 v141, v98, v99
	ds_write2_b64 v0, v[136:137], v[140:141] offset1:4
	v_cndmask_b32_e32 v0, v224, v225, vcc
	v_and_b32_e32 v100, v0, v164
	v_cmp_lt_i32_e32 vcc, 0, v163
	v_cmp_eq_u32_e64 s[6:7], 0, v100
	v_cmp_ne_u32_e64 s[4:5], 0, v100
	s_or_b64 s[6:7], vcc, s[6:7]
	s_waitcnt lgkmcnt(0)
	s_barrier
; __device__ __forceinline__ float lo2f(unsigned u) { return __uint_as_float(u << 16); }
; __device__ __forceinline__ float hi2f(unsigned u) { return __uint_as_float(u & 0xffff0000u); }
; __device__ __forceinline__ float gelu_f(float x) {
;   const float c2 = 2.f * 0.7978845608028654f * 1.4426950408889634f;
;   float p = __builtin_fmaf(x * x, 0.044715f * c2, c2);
;   float e = __builtin_amdgcn_exp2f(-x * p);
;   return x * __builtin_amdgcn_rcpf(1.f + e);
; template <int MODE>
; __device__ __forceinline__ void gemm_tile(const int ph, const int which, const int pm, const int pn) {
;     ...
;       for (int m = 0; m < 4; ++m) {
;         const int lr = ai * HALF + wr * 64 + m * 16 + fr;
;         const int gr = browC + lr;
;         const int L = gr < 32768 ? 2048 : 4096;
;         const int pos = gr & (L - 1);
;         if ((lr >= 1 || pos == 0) && (lr <= 254 || pos == L - 1)) {
;           const float s = rsv[ai][m];
;           bf16_t* arow = C + (size_t)gr * DFF;
;   #pragma unroll
;         for (int n = 0; n < 2; ++n) {
;             const int c = wc * 32 + n * 16 + fq * 4;
;             uint2 pu = make_uint2(0u, 0u), nu = make_uint2(0u, 0u);
;             if (pos != 0) pu = *(const uint2*)(Gs + (lr - 1) * 264 + c * 2);
;             if (pos != L - 1) nu = *(const uint2*)(Gs + (lr + 1) * 264 + c * 2);
;             f32x4 g = acc[ai][0][m][n], v = acc[ai][1][m][n];
;             float g0 = w0[n].x * lo2f(pu.x) + w1[n].x * (g[0] * s) + w2[n].x * lo2f(nu.x) + bb[n].x;
;             float g1 = w0[n].y * hi2f(pu.x) + w1[n].y * (g[1] * s) + w2[n].y * hi2f(nu.x) + bb[n].y;
;             float g2 = w0[n].z * lo2f(pu.y) + w1[n].z * (g[2] * s) + w2[n].z * lo2f(nu.y) + bb[n].z;
;             float g3 = w0[n].w * hi2f(pu.y) + w1[n].w * (g[3] * s) + w2[n].w * hi2f(nu.y) + bb[n].w;
;             uint2 o;
;             o.x = pack2(gelu_f(g0) * (v[0] * s), gelu_f(g1) * (v[1] * s));
;             o.y = pack2(gelu_f(g2) * (v[2] * s), gelu_f(g3) * (v[3] * s));
;             *(uint2*)(arow + ecol + c) = o;
	s_and_saveexec_b64 s[10:11], s[6:7]
	s_cbranch_execz .LBB0_414
	s_movk_i32 s6, 0xff
	v_cmp_gt_i32_e64 s[6:7], s6, v163
	v_cmp_eq_u32_e64 s[8:9], v100, v0
	v_cmp_ne_u32_e32 vcc, v100, v0
	s_or_b64 s[6:7], s[6:7], s[8:9]
	s_and_b64 exec, exec, s[6:7]
	s_cbranch_execz .LBB0_414
	v_add_u32_e32 v139, 0xfffffef8, v185
	v_mov_b32_e32 v100, 0
	v_mov_b32_e32 v136, 0
	v_mov_b32_e32 v137, 0
	s_and_saveexec_b64 s[6:7], s[4:5]
	v_lshl_add_u32 v0, v165, 1, v139
	ds_read_b64 v[136:137], v0
	s_or_b64 exec, exec, s[6:7]
	v_mov_b32_e32 v101, 0
	s_and_saveexec_b64 s[6:7], vcc
	v_lshl_add_u32 v0, v165, 1, v185
	ds_read_b64 v[100:101], v0 offset:264
	s_or_b64 exec, exec, s[6:7]
	s_waitcnt lgkmcnt(0)
	v_lshlrev_b32_e32 v142, 16, v136
	v_and_b32_e32 v143, 0xffff0000, v136
	s_waitcnt vmcnt(5)
	v_pk_mul_f32 v[142:143], v[50:51], v[142:143]
	v_lshlrev_b32_e32 v144, 16, v100
	v_pk_fma_f32 v[142:143], v[42:43], v[206:207], v[142:143]
	v_and_b32_e32 v145, 0xffff0000, v100
	v_pk_fma_f32 v[142:143], v[46:47], v[144:145], v[142:143]
	v_mov_b32_e32 v195, v194
	s_waitcnt vmcnt(3)
	v_pk_add_f32 v[142:143], v[54:55], v[142:143]
	v_pk_mul_f32 v[94:95], v[94:95], v[194:195]
	v_pk_mul_f32 v[144:145], v[142:143], v[142:143]
	v_lshlrev_b32_e32 v136, 16, v137
	v_fmamk_f32 v0, v144, 0x3dd2d3e7, v209
	v_mul_f32_e64 v0, v0, -v142
	v_exp_f32_e32 v0, v0
	v_and_b32_e32 v137, 0xffff0000, v137
	v_mov_b64_e32 v[140:141], s[2:3]
	s_movk_i32 s6, 0x1600
	v_add_f32_e32 v0, 1.0, v0
	v_rcp_f32_e32 v144, v0
	v_fmamk_f32 v0, v145, 0x3dd2d3e7, v209
	v_mul_f32_e64 v0, v0, -v143
	v_exp_f32_e32 v0, v0
	v_pk_mul_f32 v[96:97], v[96:97], v[194:195]
	v_mad_i64_i32 v[140:141], s[6:7], v164, s6, v[140:141]
	v_add_f32_e32 v0, 1.0, v0
	v_rcp_f32_e32 v145, v0
	s_nop 0
	v_pk_mul_f32 v[142:143], v[142:143], v[144:145]
	s_nop 0
	v_pk_mul_f32 v[94:95], v[94:95], v[142:143]
	s_nop 0
	v_cvt_pk_bf16_f32 v240, v94, v95
	v_pk_mul_f32 v[94:95], v[52:53], v[136:137]
	v_lshlrev_b32_e32 v136, 16, v101
	v_pk_fma_f32 v[94:95], v[44:45], v[204:205], v[94:95]
	v_and_b32_e32 v137, 0xffff0000, v101
	v_pk_fma_f32 v[94:95], v[48:49], v[136:137], v[94:95]
	s_nop 0
	v_pk_add_f32 v[94:95], v[56:57], v[94:95]
	s_nop 0
	v_pk_mul_f32 v[136:137], v[94:95], v[94:95]
	s_nop 0
	v_fmamk_f32 v0, v136, 0x3dd2d3e7, v209
	v_mul_f32_e64 v0, v0, -v94
	v_exp_f32_e32 v0, v0
	s_nop 0
	v_add_f32_e32 v0, 1.0, v0
	v_rcp_f32_e32 v136, v0
	v_fmamk_f32 v0, v137, 0x3dd2d3e7, v209
	v_mul_f32_e64 v0, v0, -v95
	v_exp_f32_e32 v0, v0
	s_nop 0
	v_add_f32_e32 v0, 1.0, v0
	v_rcp_f32_e32 v137, v0
	v_lshl_add_u32 v0, v165, 1, v244
	v_pk_mul_f32 v[94:95], v[94:95], v[136:137]
	s_nop 0
	v_pk_mul_f32 v[94:95], v[96:97], v[94:95]
	v_mov_b32_e32 v96, 0
	v_cvt_pk_bf16_f32 v241, v94, v95
	v_lshl_add_u64 v[94:95], v[140:141], 0, v[0:1]
	v_or_b32_e32 v0, 16, v165
	v_mov_b32_e32 v100, 0
	v_mov_b32_e32 v101, 0
	s_and_saveexec_b64 s[6:7], s[4:5]
	v_lshl_add_u32 v97, v0, 1, v139
	ds_read_b64 v[100:101], v97
	s_or_b64 exec, exec, s[6:7]
	v_mov_b32_e32 v97, 0
	s_and_saveexec_b64 s[4:5], vcc
	v_lshl_add_u32 v0, v0, 1, v185
	ds_read_b64 v[96:97], v0 offset:264
	s_or_b64 exec, exec, s[4:5]
	s_waitcnt lgkmcnt(0)
	v_lshlrev_b32_e32 v136, 16, v100
	v_and_b32_e32 v137, 0xffff0000, v100
	v_pk_mul_f32 v[136:137], v[26:27], v[136:137]
	v_lshlrev_b32_e32 v140, 16, v96
	s_waitcnt vmcnt(2)
	v_pk_fma_f32 v[136:137], v[38:39], v[202:203], v[136:137]
	v_and_b32_e32 v141, 0xffff0000, v96
	s_waitcnt vmcnt(1)
	v_pk_fma_f32 v[136:137], v[34:35], v[140:141], v[136:137]
	v_lshlrev_b32_e32 v100, 16, v101
	v_pk_add_f32 v[136:137], v[30:31], v[136:137]
	v_and_b32_e32 v101, 0xffff0000, v101
	v_pk_mul_f32 v[140:141], v[136:137], v[136:137]
	v_pk_mul_f32 v[100:101], v[28:29], v[100:101]
	v_fmamk_f32 v0, v140, 0x3dd2d3e7, v209
	v_mul_f32_e64 v0, v0, -v136
	v_exp_f32_e32 v0, v0
	v_pk_fma_f32 v[100:101], v[40:41], v[200:201], v[100:101]
	v_lshlrev_b32_e32 v96, 16, v97
	v_and_b32_e32 v97, 0xffff0000, v97
	v_add_f32_e32 v0, 1.0, v0
	v_rcp_f32_e32 v140, v0
	v_fmamk_f32 v0, v141, 0x3dd2d3e7, v209
	v_mul_f32_e64 v0, v0, -v137
	v_exp_f32_e32 v0, v0
	v_pk_fma_f32 v[96:97], v[36:37], v[96:97], v[100:101]
	v_pk_mul_f32 v[90:91], v[90:91], v[194:195]
	v_pk_add_f32 v[96:97], v[32:33], v[96:97]
	v_add_f32_e32 v0, 1.0, v0
	v_pk_mul_f32 v[100:101], v[96:97], v[96:97]
	v_rcp_f32_e32 v141, v0
	v_fmamk_f32 v0, v100, 0x3dd2d3e7, v209
	v_mul_f32_e64 v0, v0, -v96
	v_exp_f32_e32 v0, v0
	v_pk_mul_f32 v[136:137], v[136:137], v[140:141]
	v_pk_mul_f32 v[92:93], v[92:93], v[194:195]
	v_pk_mul_f32 v[90:91], v[90:91], v[136:137]
	v_add_f32_e32 v0, 1.0, v0
	v_rcp_f32_e32 v100, v0
	v_fmamk_f32 v0, v101, 0x3dd2d3e7, v209
	v_mul_f32_e64 v0, v0, -v97
	v_exp_f32_e32 v0, v0
	v_cvt_pk_bf16_f32 v242, v90, v91
	v_add_f32_e32 v0, 1.0, v0
	v_rcp_f32_e32 v101, v0
	s_nop 0
	v_pk_mul_f32 v[96:97], v[96:97], v[100:101]
	s_nop 0
	v_pk_mul_f32 v[92:93], v[92:93], v[96:97]
	s_nop 0
	v_cvt_pk_bf16_f32 v243, v92, v93
	s_nop 1
	v_permlane16_swap_b32_e32 v240, v242
	v_permlane16_swap_b32_e32 v241, v243
	global_store_dwordx4 v[94:95], v[240:243], off
; __device__ __forceinline__ float lo2f(unsigned u) { return __uint_as_float(u << 16); }
; __device__ __forceinline__ float hi2f(unsigned u) { return __uint_as_float(u & 0xffff0000u); }
; __device__ __forceinline__ float gelu_f(float x) {
;   const float c2 = 2.f * 0.7978845608028654f * 1.4426950408889634f;
;   float p = __builtin_fmaf(x * x, 0.044715f * c2, c2);
;   float e = __builtin_amdgcn_exp2f(-x * p);
;   return x * __builtin_amdgcn_rcpf(1.f + e);
; template <int MODE>
; __device__ __forceinline__ void gemm_tile(const int ph, const int which, const int pm, const int pn) {
;     ...
;       for (int m = 0; m < 4; ++m) {
;         const int lr = ai * HALF + wr * 64 + m * 16 + fr;
;         const int gr = browC + lr;
;         const int L = gr < 32768 ? 2048 : 4096;
;         const int pos = gr & (L - 1);
;         if ((lr >= 1 || pos == 0) && (lr <= 254 || pos == L - 1)) {
;           const float s = rsv[ai][m];
;           bf16_t* arow = C + (size_t)gr * DFF;
;   #pragma unroll
;         for (int n = 0; n < 2; ++n) {
;             const int c = wc * 32 + n * 16 + fq * 4;
;             uint2 pu = make_uint2(0u, 0u), nu = make_uint2(0u, 0u);
;             if (pos != 0) pu = *(const uint2*)(Gs + (lr - 1) * 264 + c * 2);
;             if (pos != L - 1) nu = *(const uint2*)(Gs + (lr + 1) * 264 + c * 2);
;             f32x4 g = acc[ai][0][m][n], v = acc[ai][1][m][n];
;             float g0 = w0[n].x * lo2f(pu.x) + w1[n].x * (g[0] * s) + w2[n].x * lo2f(nu.x) + bb[n].x;
;             float g1 = w0[n].y * hi2f(pu.x) + w1[n].y * (g[1] * s) + w2[n].y * hi2f(nu.x) + bb[n].y;
;             float g2 = w0[n].z * lo2f(pu.y) + w1[n].z * (g[2] * s) + w2[n].z * lo2f(nu.y) + bb[n].z;
;             float g3 = w0[n].w * hi2f(pu.y) + w1[n].w * (g[3] * s) + w2[n].w * hi2f(nu.y) + bb[n].w;
;             uint2 o;
;             o.x = pack2(gelu_f(g0) * (v[0] * s), gelu_f(g1) * (v[1] * s));
;             o.y = pack2(gelu_f(g2) * (v[2] * s), gelu_f(g3) * (v[3] * s));
;             *(uint2*)(arow + ecol + c) = o;
.LBB0_414:
	s_or_b64 exec, exec, s[10:11]
	v_or_b32_e32 v90, 16, v163
	v_add_u32_e32 v0, s26, v90
	v_cmp_gt_i32_e32 vcc, s36, v0
	s_nop 1
	v_cndmask_b32_e32 v91, v224, v225, vcc
	v_and_b32_e32 v92, v91, v0
	v_cmp_lt_i32_e32 vcc, -1, v167
	v_cmp_eq_u32_e64 s[4:5], 0, v92
	v_cmp_ne_u32_e64 s[6:7], 0, v92
	s_or_b64 s[4:5], vcc, s[4:5]
	s_and_saveexec_b64 s[16:17], s[4:5]
	s_cbranch_execz .LBB0_425
	s_movk_i32 s4, 0xff
	v_cmp_gt_i32_e64 s[8:9], s4, v90
	v_cmp_eq_u32_e64 s[10:11], v92, v91
	v_cmp_ne_u32_e64 s[4:5], v92, v91
	s_or_b64 s[8:9], s[8:9], s[10:11]
	s_and_b64 exec, exec, s[8:9]
	s_cbranch_execz .LBB0_425
	v_add_u32_e32 v94, 0xfffffef8, v175
	v_mov_b32_e32 v90, 0
	v_mov_b32_e32 v92, 0
	v_mov_b32_e32 v93, 0
	s_and_saveexec_b64 s[8:9], s[6:7]
	v_lshl_add_u32 v91, v165, 1, v94
	ds_read_b64 v[92:93], v91
	s_or_b64 exec, exec, s[8:9]
	v_mov_b32_e32 v91, 0
	s_and_saveexec_b64 s[8:9], s[4:5]
	v_lshl_add_u32 v90, v165, 1, v175
	ds_read_b64 v[90:91], v90 offset:264
	s_or_b64 exec, exec, s[8:9]
	s_waitcnt lgkmcnt(0)
	v_lshlrev_b32_e32 v100, 16, v92
	v_and_b32_e32 v101, 0xffff0000, v92
	s_waitcnt vmcnt(5)
	v_pk_mul_f32 v[100:101], v[50:51], v[100:101]
	v_lshlrev_b32_e32 v136, 16, v90
	v_pk_fma_f32 v[100:101], v[42:43], v[198:199], v[100:101]
	v_and_b32_e32 v137, 0xffff0000, v90
	v_pk_fma_f32 v[100:101], v[46:47], v[136:137], v[100:101]
	v_mov_b64_e32 v[96:97], s[2:3]
	s_waitcnt vmcnt(3)
	v_pk_add_f32 v[100:101], v[54:55], v[100:101]
	s_movk_i32 s8, 0x1600
	v_pk_mul_f32 v[136:137], v[100:101], v[100:101]
	v_mad_i64_i32 v[96:97], s[8:9], v0, s8, v[96:97]
	v_fmamk_f32 v0, v136, 0x3dd2d3e7, v209
	v_mul_f32_e64 v0, v0, -v100
	v_exp_f32_e32 v0, v0
	v_mov_b32_e32 v185, v184
	v_pk_mul_f32 v[86:87], v[86:87], v[184:185]
	v_lshlrev_b32_e32 v92, 16, v93
	v_add_f32_e32 v0, 1.0, v0
	v_rcp_f32_e32 v136, v0
	v_fmamk_f32 v0, v137, 0x3dd2d3e7, v209
	v_mul_f32_e64 v0, v0, -v101
	v_exp_f32_e32 v0, v0
	v_and_b32_e32 v93, 0xffff0000, v93
	v_pk_mul_f32 v[88:89], v[88:89], v[184:185]
	v_add_f32_e32 v0, 1.0, v0
	v_rcp_f32_e32 v137, v0
	s_nop 0
	v_pk_mul_f32 v[100:101], v[100:101], v[136:137]
	s_nop 0
	v_pk_mul_f32 v[86:87], v[86:87], v[100:101]
	s_nop 0
	v_cvt_pk_bf16_f32 v240, v86, v87
	v_pk_mul_f32 v[86:87], v[52:53], v[92:93]
	v_lshlrev_b32_e32 v92, 16, v91
	v_pk_fma_f32 v[86:87], v[44:45], v[196:197], v[86:87]
	v_and_b32_e32 v93, 0xffff0000, v91
	v_pk_fma_f32 v[86:87], v[48:49], v[92:93], v[86:87]
	s_nop 0
	v_pk_add_f32 v[86:87], v[56:57], v[86:87]
	s_nop 0
	v_pk_mul_f32 v[92:93], v[86:87], v[86:87]
	s_nop 0
	v_fmamk_f32 v0, v92, 0x3dd2d3e7, v209
	v_mul_f32_e64 v0, v0, -v86
	v_exp_f32_e32 v0, v0
	s_nop 0
	v_add_f32_e32 v0, 1.0, v0
	v_rcp_f32_e32 v92, v0
	v_fmamk_f32 v0, v93, 0x3dd2d3e7, v209
	v_mul_f32_e64 v0, v0, -v87
	v_exp_f32_e32 v0, v0
	s_nop 0
	v_add_f32_e32 v0, 1.0, v0
	v_rcp_f32_e32 v93, v0
	v_lshl_add_u32 v0, v165, 1, v244
	v_pk_mul_f32 v[86:87], v[86:87], v[92:93]
	s_nop 0
	v_pk_mul_f32 v[86:87], v[88:89], v[86:87]
	v_mov_b32_e32 v88, 0
	v_cvt_pk_bf16_f32 v241, v86, v87
	v_lshl_add_u64 v[86:87], v[96:97], 0, v[0:1]
	v_or_b32_e32 v0, 16, v165
	v_mov_b32_e32 v90, 0
	v_mov_b32_e32 v91, 0
	s_and_saveexec_b64 s[8:9], s[6:7]
	v_lshl_add_u32 v89, v0, 1, v94
	ds_read_b64 v[90:91], v89
	s_or_b64 exec, exec, s[8:9]
	v_mov_b32_e32 v89, 0
	s_and_saveexec_b64 s[6:7], s[4:5]
	v_lshl_add_u32 v0, v0, 1, v175
	ds_read_b64 v[88:89], v0 offset:264
	s_or_b64 exec, exec, s[6:7]
	s_waitcnt lgkmcnt(0)
	v_lshlrev_b32_e32 v92, 16, v90
	v_and_b32_e32 v93, 0xffff0000, v90
	v_pk_mul_f32 v[92:93], v[26:27], v[92:93]
	v_lshlrev_b32_e32 v94, 16, v88
	s_waitcnt vmcnt(2)
	v_pk_fma_f32 v[92:93], v[38:39], v[192:193], v[92:93]
	v_and_b32_e32 v95, 0xffff0000, v88
	s_waitcnt vmcnt(1)
	v_pk_fma_f32 v[92:93], v[34:35], v[94:95], v[92:93]
	v_lshlrev_b32_e32 v90, 16, v91
	v_pk_add_f32 v[92:93], v[30:31], v[92:93]
	v_and_b32_e32 v91, 0xffff0000, v91
	v_pk_mul_f32 v[94:95], v[92:93], v[92:93]
	v_pk_mul_f32 v[90:91], v[28:29], v[90:91]
	v_fmamk_f32 v0, v94, 0x3dd2d3e7, v209
	v_mul_f32_e64 v0, v0, -v92
	v_exp_f32_e32 v0, v0
	v_pk_fma_f32 v[90:91], v[40:41], v[190:191], v[90:91]
	v_lshlrev_b32_e32 v88, 16, v89
	v_and_b32_e32 v89, 0xffff0000, v89
	v_add_f32_e32 v0, 1.0, v0
	v_rcp_f32_e32 v94, v0
	v_fmamk_f32 v0, v95, 0x3dd2d3e7, v209
	v_mul_f32_e64 v0, v0, -v93
	v_exp_f32_e32 v0, v0
	v_pk_fma_f32 v[88:89], v[36:37], v[88:89], v[90:91]
	v_pk_mul_f32 v[82:83], v[82:83], v[184:185]
	v_pk_add_f32 v[88:89], v[32:33], v[88:89]
	v_add_f32_e32 v0, 1.0, v0
	v_pk_mul_f32 v[90:91], v[88:89], v[88:89]
	v_rcp_f32_e32 v95, v0
	v_fmamk_f32 v0, v90, 0x3dd2d3e7, v209
	v_mul_f32_e64 v0, v0, -v88
	v_exp_f32_e32 v0, v0
	v_pk_mul_f32 v[92:93], v[92:93], v[94:95]
	v_pk_mul_f32 v[84:85], v[84:85], v[184:185]
	v_pk_mul_f32 v[82:83], v[82:83], v[92:93]
	v_add_f32_e32 v0, 1.0, v0
	v_rcp_f32_e32 v90, v0
	v_fmamk_f32 v0, v91, 0x3dd2d3e7, v209
	v_mul_f32_e64 v0, v0, -v89
	v_exp_f32_e32 v0, v0
	v_cvt_pk_bf16_f32 v242, v82, v83
	v_add_f32_e32 v0, 1.0, v0
	v_rcp_f32_e32 v91, v0
	s_nop 0
	v_pk_mul_f32 v[88:89], v[88:89], v[90:91]
	s_nop 0
	v_pk_mul_f32 v[84:85], v[84:85], v[88:89]
	s_nop 0
	v_cvt_pk_bf16_f32 v243, v84, v85
	s_nop 1
	v_permlane16_swap_b32_e32 v240, v242
	v_permlane16_swap_b32_e32 v241, v243
	global_store_dwordx4 v[86:87], v[240:243], off
; __device__ __forceinline__ float lo2f(unsigned u) { return __uint_as_float(u << 16); }
; __device__ __forceinline__ float hi2f(unsigned u) { return __uint_as_float(u & 0xffff0000u); }
; __device__ __forceinline__ float gelu_f(float x) {
;   const float c2 = 2.f * 0.7978845608028654f * 1.4426950408889634f;
;   float p = __builtin_fmaf(x * x, 0.044715f * c2, c2);
;   float e = __builtin_amdgcn_exp2f(-x * p);
;   return x * __builtin_amdgcn_rcpf(1.f + e);
; template <int MODE>
; __device__ __forceinline__ void gemm_tile(const int ph, const int which, const int pm, const int pn) {
;     ...
;       for (int m = 0; m < 4; ++m) {
;         const int lr = ai * HALF + wr * 64 + m * 16 + fr;
;         const int gr = browC + lr;
;         const int L = gr < 32768 ? 2048 : 4096;
;         const int pos = gr & (L - 1);
;         if ((lr >= 1 || pos == 0) && (lr <= 254 || pos == L - 1)) {
;           const float s = rsv[ai][m];
;           bf16_t* arow = C + (size_t)gr * DFF;
;   #pragma unroll
;         for (int n = 0; n < 2; ++n) {
;             const int c = wc * 32 + n * 16 + fq * 4;
;             uint2 pu = make_uint2(0u, 0u), nu = make_uint2(0u, 0u);
;             if (pos != 0) pu = *(const uint2*)(Gs + (lr - 1) * 264 + c * 2);
;             if (pos != L - 1) nu = *(const uint2*)(Gs + (lr + 1) * 264 + c * 2);
;             f32x4 g = acc[ai][0][m][n], v = acc[ai][1][m][n];
;             float g0 = w0[n].x * lo2f(pu.x) + w1[n].x * (g[0] * s) + w2[n].x * lo2f(nu.x) + bb[n].x;
;             float g1 = w0[n].y * hi2f(pu.x) + w1[n].y * (g[1] * s) + w2[n].y * hi2f(nu.x) + bb[n].y;
;             float g2 = w0[n].z * lo2f(pu.y) + w1[n].z * (g[2] * s) + w2[n].z * lo2f(nu.y) + bb[n].z;
;             float g3 = w0[n].w * hi2f(pu.y) + w1[n].w * (g[3] * s) + w2[n].w * hi2f(nu.y) + bb[n].w;
;             uint2 o;
;             o.x = pack2(gelu_f(g0) * (v[0] * s), gelu_f(g1) * (v[1] * s));
;             o.y = pack2(gelu_f(g2) * (v[2] * s), gelu_f(g3) * (v[3] * s));
;             *(uint2*)(arow + ecol + c) = o;
.LBB0_425:
	s_or_b64 exec, exec, s[16:17]
	v_or_b32_e32 v82, 32, v163
	v_add_u32_e32 v0, s26, v82
	v_cmp_gt_i32_e64 s[4:5], s36, v0
	s_nop 1
	v_cndmask_b32_e64 v83, v224, v225, s[4:5]
	v_and_b32_e32 v84, v83, v0
	v_cmp_eq_u32_e64 s[4:5], 0, v84
	v_cmp_ne_u32_e64 s[6:7], 0, v84
	s_or_b64 s[4:5], vcc, s[4:5]
	s_and_saveexec_b64 s[16:17], s[4:5]
	s_cbranch_execz .LBB0_436
	s_movk_i32 s4, 0xff
	v_cmp_gt_i32_e64 s[8:9], s4, v82
	v_cmp_eq_u32_e64 s[10:11], v84, v83
	v_cmp_ne_u32_e64 s[4:5], v84, v83
	s_or_b64 s[8:9], s[8:9], s[10:11]
	s_and_b64 exec, exec, s[8:9]
	s_cbranch_execz .LBB0_436
	v_add_u32_e32 v86, 0xfffffef8, v173
	v_mov_b32_e32 v82, 0
	v_mov_b32_e32 v84, 0
	v_mov_b32_e32 v85, 0
	s_and_saveexec_b64 s[8:9], s[6:7]
	v_lshl_add_u32 v83, v165, 1, v86
	ds_read_b64 v[84:85], v83
	s_or_b64 exec, exec, s[8:9]
	v_mov_b32_e32 v83, 0
	s_and_saveexec_b64 s[8:9], s[4:5]
	v_lshl_add_u32 v82, v165, 1, v173
	ds_read_b64 v[82:83], v82 offset:264
	s_or_b64 exec, exec, s[8:9]
	s_waitcnt lgkmcnt(0)
	v_lshlrev_b32_e32 v90, 16, v84
	v_and_b32_e32 v91, 0xffff0000, v84
	s_waitcnt vmcnt(5)
	v_pk_mul_f32 v[90:91], v[50:51], v[90:91]
	v_lshlrev_b32_e32 v92, 16, v82
	v_pk_fma_f32 v[90:91], v[42:43], v[188:189], v[90:91]
	v_and_b32_e32 v93, 0xffff0000, v82
	v_pk_fma_f32 v[90:91], v[46:47], v[92:93], v[90:91]
	v_mov_b64_e32 v[88:89], s[2:3]
	s_waitcnt vmcnt(3)
	v_pk_add_f32 v[90:91], v[54:55], v[90:91]
	s_movk_i32 s8, 0x1600
	v_pk_mul_f32 v[92:93], v[90:91], v[90:91]
	v_mad_i64_i32 v[88:89], s[8:9], v0, s8, v[88:89]
	v_fmamk_f32 v0, v92, 0x3dd2d3e7, v209
	v_mul_f32_e64 v0, v0, -v90
	v_exp_f32_e32 v0, v0
	v_mov_b32_e32 v175, v174
	v_pk_mul_f32 v[78:79], v[78:79], v[174:175]
	v_lshlrev_b32_e32 v84, 16, v85
	v_add_f32_e32 v0, 1.0, v0
	v_rcp_f32_e32 v92, v0
	v_fmamk_f32 v0, v93, 0x3dd2d3e7, v209
	v_mul_f32_e64 v0, v0, -v91
	v_exp_f32_e32 v0, v0
	v_and_b32_e32 v85, 0xffff0000, v85
	v_pk_mul_f32 v[80:81], v[80:81], v[174:175]
	v_add_f32_e32 v0, 1.0, v0
	v_rcp_f32_e32 v93, v0
	s_nop 0
	v_pk_mul_f32 v[90:91], v[90:91], v[92:93]
	s_nop 0
	v_pk_mul_f32 v[78:79], v[78:79], v[90:91]
	s_nop 0
	v_cvt_pk_bf16_f32 v240, v78, v79
	v_pk_mul_f32 v[78:79], v[52:53], v[84:85]
	v_lshlrev_b32_e32 v84, 16, v83
	v_pk_fma_f32 v[78:79], v[44:45], v[186:187], v[78:79]
	v_and_b32_e32 v85, 0xffff0000, v83
	v_pk_fma_f32 v[78:79], v[48:49], v[84:85], v[78:79]
	s_nop 0
	v_pk_add_f32 v[78:79], v[56:57], v[78:79]
	s_nop 0
	v_pk_mul_f32 v[84:85], v[78:79], v[78:79]
	s_nop 0
	v_fmamk_f32 v0, v84, 0x3dd2d3e7, v209
	v_mul_f32_e64 v0, v0, -v78
	v_exp_f32_e32 v0, v0
	s_nop 0
	v_add_f32_e32 v0, 1.0, v0
	v_rcp_f32_e32 v84, v0
	v_fmamk_f32 v0, v85, 0x3dd2d3e7, v209
	v_mul_f32_e64 v0, v0, -v79
	v_exp_f32_e32 v0, v0
	s_nop 0
	v_add_f32_e32 v0, 1.0, v0
	v_rcp_f32_e32 v85, v0
	v_lshl_add_u32 v0, v165, 1, v244
	v_pk_mul_f32 v[78:79], v[78:79], v[84:85]
	s_nop 0
	v_pk_mul_f32 v[78:79], v[80:81], v[78:79]
	v_mov_b32_e32 v80, 0
	v_cvt_pk_bf16_f32 v241, v78, v79
	v_lshl_add_u64 v[78:79], v[88:89], 0, v[0:1]
	v_or_b32_e32 v0, 16, v165
	v_mov_b32_e32 v82, 0
	v_mov_b32_e32 v83, 0
	s_and_saveexec_b64 s[8:9], s[6:7]
	v_lshl_add_u32 v81, v0, 1, v86
	ds_read_b64 v[82:83], v81
	s_or_b64 exec, exec, s[8:9]
	v_mov_b32_e32 v81, 0
	s_and_saveexec_b64 s[6:7], s[4:5]
	v_lshl_add_u32 v0, v0, 1, v173
	ds_read_b64 v[80:81], v0 offset:264
	s_or_b64 exec, exec, s[6:7]
	s_waitcnt lgkmcnt(0)
	v_lshlrev_b32_e32 v84, 16, v82
	v_and_b32_e32 v85, 0xffff0000, v82
	v_pk_mul_f32 v[84:85], v[26:27], v[84:85]
	v_lshlrev_b32_e32 v86, 16, v80
	s_waitcnt vmcnt(2)
	v_pk_fma_f32 v[84:85], v[38:39], v[182:183], v[84:85]
	v_and_b32_e32 v87, 0xffff0000, v80
	s_waitcnt vmcnt(1)
	v_pk_fma_f32 v[84:85], v[34:35], v[86:87], v[84:85]
	v_lshlrev_b32_e32 v82, 16, v83
	v_pk_add_f32 v[84:85], v[30:31], v[84:85]
	v_and_b32_e32 v83, 0xffff0000, v83
	v_pk_mul_f32 v[86:87], v[84:85], v[84:85]
	v_pk_mul_f32 v[82:83], v[28:29], v[82:83]
	v_fmamk_f32 v0, v86, 0x3dd2d3e7, v209
	v_mul_f32_e64 v0, v0, -v84
	v_exp_f32_e32 v0, v0
	v_pk_fma_f32 v[82:83], v[40:41], v[180:181], v[82:83]
	v_lshlrev_b32_e32 v80, 16, v81
	v_and_b32_e32 v81, 0xffff0000, v81
	v_add_f32_e32 v0, 1.0, v0
	v_rcp_f32_e32 v86, v0
	v_fmamk_f32 v0, v87, 0x3dd2d3e7, v209
	v_mul_f32_e64 v0, v0, -v85
	v_exp_f32_e32 v0, v0
	v_pk_fma_f32 v[80:81], v[36:37], v[80:81], v[82:83]
	v_pk_mul_f32 v[74:75], v[74:75], v[174:175]
	v_pk_add_f32 v[80:81], v[32:33], v[80:81]
	v_add_f32_e32 v0, 1.0, v0
	v_pk_mul_f32 v[82:83], v[80:81], v[80:81]
	v_rcp_f32_e32 v87, v0
	v_fmamk_f32 v0, v82, 0x3dd2d3e7, v209
	v_mul_f32_e64 v0, v0, -v80
	v_exp_f32_e32 v0, v0
	v_pk_mul_f32 v[84:85], v[84:85], v[86:87]
	v_pk_mul_f32 v[76:77], v[76:77], v[174:175]
	v_pk_mul_f32 v[74:75], v[74:75], v[84:85]
	v_add_f32_e32 v0, 1.0, v0
	v_rcp_f32_e32 v82, v0
	v_fmamk_f32 v0, v83, 0x3dd2d3e7, v209
	v_mul_f32_e64 v0, v0, -v81
	v_exp_f32_e32 v0, v0
	v_cvt_pk_bf16_f32 v242, v74, v75
	v_add_f32_e32 v0, 1.0, v0
	v_rcp_f32_e32 v83, v0
	s_nop 0
	v_pk_mul_f32 v[80:81], v[80:81], v[82:83]
	s_nop 0
	v_pk_mul_f32 v[76:77], v[76:77], v[80:81]
	s_nop 0
	v_cvt_pk_bf16_f32 v243, v76, v77
	s_nop 1
	v_permlane16_swap_b32_e32 v240, v242
	v_permlane16_swap_b32_e32 v241, v243
	global_store_dwordx4 v[78:79], v[240:243], off
; __device__ __forceinline__ float lo2f(unsigned u) { return __uint_as_float(u << 16); }
; __device__ __forceinline__ float hi2f(unsigned u) { return __uint_as_float(u & 0xffff0000u); }
; __device__ __forceinline__ float gelu_f(float x) {
;   const float c2 = 2.f * 0.7978845608028654f * 1.4426950408889634f;
;   float p = __builtin_fmaf(x * x, 0.044715f * c2, c2);
;   float e = __builtin_amdgcn_exp2f(-x * p);
;   return x * __builtin_amdgcn_rcpf(1.f + e);
; template <int MODE>
; __device__ __forceinline__ void gemm_tile(const int ph, const int which, const int pm, const int pn) {
;     ...
;       for (int m = 0; m < 4; ++m) {
;         const int lr = ai * HALF + wr * 64 + m * 16 + fr;
;         const int gr = browC + lr;
;         const int L = gr < 32768 ? 2048 : 4096;
;         const int pos = gr & (L - 1);
;         if ((lr >= 1 || pos == 0) && (lr <= 254 || pos == L - 1)) {
;           const float s = rsv[ai][m];
;           bf16_t* arow = C + (size_t)gr * DFF;
;   #pragma unroll
;         for (int n = 0; n < 2; ++n) {
;             const int c = wc * 32 + n * 16 + fq * 4;
;             uint2 pu = make_uint2(0u, 0u), nu = make_uint2(0u, 0u);
;             if (pos != 0) pu = *(const uint2*)(Gs + (lr - 1) * 264 + c * 2);
;             if (pos != L - 1) nu = *(const uint2*)(Gs + (lr + 1) * 264 + c * 2);
;             f32x4 g = acc[ai][0][m][n], v = acc[ai][1][m][n];
;             float g0 = w0[n].x * lo2f(pu.x) + w1[n].x * (g[0] * s) + w2[n].x * lo2f(nu.x) + bb[n].x;
;             float g1 = w0[n].y * hi2f(pu.x) + w1[n].y * (g[1] * s) + w2[n].y * hi2f(nu.x) + bb[n].y;
;             float g2 = w0[n].z * lo2f(pu.y) + w1[n].z * (g[2] * s) + w2[n].z * lo2f(nu.y) + bb[n].z;
;             float g3 = w0[n].w * hi2f(pu.y) + w1[n].w * (g[3] * s) + w2[n].w * hi2f(nu.y) + bb[n].w;
;             uint2 o;
;             o.x = pack2(gelu_f(g0) * (v[0] * s), gelu_f(g1) * (v[1] * s));
;             o.y = pack2(gelu_f(g2) * (v[2] * s), gelu_f(g3) * (v[3] * s));
;             *(uint2*)(arow + ecol + c) = o;
.LBB0_436:
	s_or_b64 exec, exec, s[16:17]
	v_or_b32_e32 v74, 48, v163
	v_add_u32_e32 v0, s26, v74
	v_cmp_gt_i32_e64 s[4:5], s36, v0
	s_nop 1
	v_cndmask_b32_e64 v75, v224, v225, s[4:5]
	v_and_b32_e32 v76, v75, v0
	v_cmp_eq_u32_e64 s[6:7], 0, v76
	v_cmp_ne_u32_e64 s[4:5], 0, v76
	s_or_b64 s[6:7], vcc, s[6:7]
	s_and_saveexec_b64 s[10:11], s[6:7]
	s_cbranch_execz .LBB0_447
	s_movk_i32 s6, 0xff
	v_cmp_gt_i32_e64 s[6:7], s6, v74
	v_cmp_eq_u32_e64 s[8:9], v76, v75
	v_cmp_ne_u32_e32 vcc, v76, v75
	s_or_b64 s[6:7], s[6:7], s[8:9]
	s_and_b64 exec, exec, s[6:7]
	s_cbranch_execz .LBB0_447
	v_add_u32_e32 v78, 0xfffffef8, v171
	v_mov_b32_e32 v74, 0
	v_mov_b32_e32 v76, 0
	v_mov_b32_e32 v77, 0
	s_and_saveexec_b64 s[6:7], s[4:5]
	v_lshl_add_u32 v75, v165, 1, v78
	ds_read_b64 v[76:77], v75
	s_or_b64 exec, exec, s[6:7]
	v_mov_b32_e32 v75, 0
	s_and_saveexec_b64 s[6:7], vcc
	v_lshl_add_u32 v74, v165, 1, v171
	ds_read_b64 v[74:75], v74 offset:264
	s_or_b64 exec, exec, s[6:7]
	s_waitcnt lgkmcnt(0)
	v_lshlrev_b32_e32 v82, 16, v76
	v_and_b32_e32 v83, 0xffff0000, v76
	s_waitcnt vmcnt(5)
	v_pk_mul_f32 v[82:83], v[50:51], v[82:83]
	v_lshlrev_b32_e32 v84, 16, v74
	v_pk_fma_f32 v[82:83], v[42:43], v[178:179], v[82:83]
	v_and_b32_e32 v85, 0xffff0000, v74
	v_pk_fma_f32 v[82:83], v[46:47], v[84:85], v[82:83]
	v_mov_b64_e32 v[80:81], s[2:3]
	s_waitcnt vmcnt(3)
	v_pk_add_f32 v[82:83], v[54:55], v[82:83]
	s_movk_i32 s6, 0x1600
	v_pk_mul_f32 v[84:85], v[82:83], v[82:83]
	v_mad_i64_i32 v[80:81], s[6:7], v0, s6, v[80:81]
	v_fmamk_f32 v0, v84, 0x3dd2d3e7, v209
	v_mul_f32_e64 v0, v0, -v82
	v_exp_f32_e32 v0, v0
	v_mov_b32_e32 v173, v172
	v_pk_mul_f32 v[70:71], v[70:71], v[172:173]
	v_lshlrev_b32_e32 v76, 16, v77
	v_add_f32_e32 v0, 1.0, v0
	v_rcp_f32_e32 v84, v0
	v_fmamk_f32 v0, v85, 0x3dd2d3e7, v209
	v_mul_f32_e64 v0, v0, -v83
	v_exp_f32_e32 v0, v0
	v_and_b32_e32 v77, 0xffff0000, v77
	v_pk_mul_f32 v[72:73], v[72:73], v[172:173]
	v_add_f32_e32 v0, 1.0, v0
	v_rcp_f32_e32 v85, v0
	s_nop 0
	v_pk_mul_f32 v[82:83], v[82:83], v[84:85]
	s_nop 0
	v_pk_mul_f32 v[70:71], v[70:71], v[82:83]
	s_nop 0
	v_cvt_pk_bf16_f32 v240, v70, v71
	v_pk_mul_f32 v[70:71], v[52:53], v[76:77]
	v_lshlrev_b32_e32 v76, 16, v75
	v_pk_fma_f32 v[70:71], v[44:45], v[176:177], v[70:71]
	v_and_b32_e32 v77, 0xffff0000, v75
	v_pk_fma_f32 v[70:71], v[48:49], v[76:77], v[70:71]
	s_nop 0
	v_pk_add_f32 v[70:71], v[56:57], v[70:71]
	s_nop 0
	v_pk_mul_f32 v[76:77], v[70:71], v[70:71]
	s_nop 0
	v_fmamk_f32 v0, v76, 0x3dd2d3e7, v209
	v_mul_f32_e64 v0, v0, -v70
	v_exp_f32_e32 v0, v0
	s_nop 0
	v_add_f32_e32 v0, 1.0, v0
	v_rcp_f32_e32 v76, v0
	v_fmamk_f32 v0, v77, 0x3dd2d3e7, v209
	v_mul_f32_e64 v0, v0, -v71
	v_exp_f32_e32 v0, v0
	s_nop 0
	v_add_f32_e32 v0, 1.0, v0
	v_rcp_f32_e32 v77, v0
	v_lshl_add_u32 v0, v165, 1, v244
	v_pk_mul_f32 v[70:71], v[70:71], v[76:77]
	s_nop 0
	v_pk_mul_f32 v[70:71], v[72:73], v[70:71]
	v_mov_b32_e32 v72, 0
	v_cvt_pk_bf16_f32 v241, v70, v71
	v_lshl_add_u64 v[70:71], v[80:81], 0, v[0:1]
	v_or_b32_e32 v0, 16, v165
	v_mov_b32_e32 v74, 0
	v_mov_b32_e32 v75, 0
	s_and_saveexec_b64 s[6:7], s[4:5]
	v_lshl_add_u32 v73, v0, 1, v78
	ds_read_b64 v[74:75], v73
	s_or_b64 exec, exec, s[6:7]
	v_mov_b32_e32 v73, 0
	s_and_saveexec_b64 s[4:5], vcc
	v_lshl_add_u32 v0, v0, 1, v171
	ds_read_b64 v[72:73], v0 offset:264
	s_or_b64 exec, exec, s[4:5]
	s_waitcnt lgkmcnt(0)
	v_lshlrev_b32_e32 v76, 16, v74
	v_and_b32_e32 v77, 0xffff0000, v74
	v_pk_mul_f32 v[76:77], v[26:27], v[76:77]
	v_lshlrev_b32_e32 v78, 16, v72
	s_waitcnt vmcnt(2)
	v_pk_fma_f32 v[76:77], v[38:39], v[134:135], v[76:77]
	v_and_b32_e32 v79, 0xffff0000, v72
	s_waitcnt vmcnt(1)
	v_pk_fma_f32 v[76:77], v[34:35], v[78:79], v[76:77]
	v_lshlrev_b32_e32 v74, 16, v75
	v_pk_add_f32 v[76:77], v[30:31], v[76:77]
	v_and_b32_e32 v75, 0xffff0000, v75
	v_pk_mul_f32 v[78:79], v[76:77], v[76:77]
	v_pk_mul_f32 v[74:75], v[28:29], v[74:75]
	v_fmamk_f32 v0, v78, 0x3dd2d3e7, v209
	v_mul_f32_e64 v0, v0, -v76
	v_exp_f32_e32 v0, v0
	v_pk_fma_f32 v[74:75], v[40:41], v[132:133], v[74:75]
	v_lshlrev_b32_e32 v72, 16, v73
	v_and_b32_e32 v73, 0xffff0000, v73
	v_add_f32_e32 v0, 1.0, v0
	v_rcp_f32_e32 v78, v0
	v_fmamk_f32 v0, v79, 0x3dd2d3e7, v209
	v_mul_f32_e64 v0, v0, -v77
	v_exp_f32_e32 v0, v0
	v_pk_fma_f32 v[72:73], v[36:37], v[72:73], v[74:75]
	v_pk_mul_f32 v[66:67], v[66:67], v[172:173]
	v_pk_add_f32 v[72:73], v[32:33], v[72:73]
	v_add_f32_e32 v0, 1.0, v0
	v_pk_mul_f32 v[74:75], v[72:73], v[72:73]
	v_rcp_f32_e32 v79, v0
	v_fmamk_f32 v0, v74, 0x3dd2d3e7, v209
	v_mul_f32_e64 v0, v0, -v72
	v_exp_f32_e32 v0, v0
	v_pk_mul_f32 v[76:77], v[76:77], v[78:79]
	v_pk_mul_f32 v[68:69], v[68:69], v[172:173]
	v_pk_mul_f32 v[66:67], v[66:67], v[76:77]
	v_add_f32_e32 v0, 1.0, v0
	v_rcp_f32_e32 v74, v0
	v_fmamk_f32 v0, v75, 0x3dd2d3e7, v209
	v_mul_f32_e64 v0, v0, -v73
	v_exp_f32_e32 v0, v0
	v_cvt_pk_bf16_f32 v242, v66, v67
	v_add_f32_e32 v0, 1.0, v0
	v_rcp_f32_e32 v75, v0
	s_nop 0
	v_pk_mul_f32 v[72:73], v[72:73], v[74:75]
	s_nop 0
	v_pk_mul_f32 v[68:69], v[68:69], v[72:73]
	s_nop 0
	v_cvt_pk_bf16_f32 v243, v68, v69
	s_nop 1
	v_permlane16_swap_b32_e32 v240, v242
	v_permlane16_swap_b32_e32 v241, v243
	global_store_dwordx4 v[70:71], v[240:243], off
; __device__ __forceinline__ float lo2f(unsigned u) { return __uint_as_float(u << 16); }
; __device__ __forceinline__ float hi2f(unsigned u) { return __uint_as_float(u & 0xffff0000u); }
; __device__ __forceinline__ float gelu_f(float x) {
;   const float c2 = 2.f * 0.7978845608028654f * 1.4426950408889634f;
;   float p = __builtin_fmaf(x * x, 0.044715f * c2, c2);
;   float e = __builtin_amdgcn_exp2f(-x * p);
;   return x * __builtin_amdgcn_rcpf(1.f + e);
; template <int MODE>
; __device__ __forceinline__ void gemm_tile(const int ph, const int which, const int pm, const int pn) {
;     ...
;       for (int m = 0; m < 4; ++m) {
;         const int lr = ai * HALF + wr * 64 + m * 16 + fr;
;         const int gr = browC + lr;
;         const int L = gr < 32768 ? 2048 : 4096;
;         const int pos = gr & (L - 1);
;         if ((lr >= 1 || pos == 0) && (lr <= 254 || pos == L - 1)) {
;           const float s = rsv[ai][m];
;           bf16_t* arow = C + (size_t)gr * DFF;
;   #pragma unroll
;         for (int n = 0; n < 2; ++n) {
;             const int c = wc * 32 + n * 16 + fq * 4;
;             uint2 pu = make_uint2(0u, 0u), nu = make_uint2(0u, 0u);
;             if (pos != 0) pu = *(const uint2*)(Gs + (lr - 1) * 264 + c * 2);
;             if (pos != L - 1) nu = *(const uint2*)(Gs + (lr + 1) * 264 + c * 2);
;             f32x4 g = acc[ai][0][m][n], v = acc[ai][1][m][n];
;             float g0 = w0[n].x * lo2f(pu.x) + w1[n].x * (g[0] * s) + w2[n].x * lo2f(nu.x) + bb[n].x;
;             float g1 = w0[n].y * hi2f(pu.x) + w1[n].y * (g[1] * s) + w2[n].y * hi2f(nu.x) + bb[n].y;
;             float g2 = w0[n].z * lo2f(pu.y) + w1[n].z * (g[2] * s) + w2[n].z * lo2f(nu.y) + bb[n].z;
;             float g3 = w0[n].w * hi2f(pu.y) + w1[n].w * (g[3] * s) + w2[n].w * hi2f(nu.y) + bb[n].w;
;             uint2 o;
;             o.x = pack2(gelu_f(g0) * (v[0] * s), gelu_f(g1) * (v[1] * s));
;             o.y = pack2(gelu_f(g2) * (v[2] * s), gelu_f(g3) * (v[3] * s));
;             *(uint2*)(arow + ecol + c) = o;
.LBB0_447:
	s_or_b64 exec, exec, s[10:11]
	v_add_u32_e32 v0, 0x80, v164
	v_cmp_gt_i32_e32 vcc, s36, v0
	s_movk_i32 s4, 0xff80
	s_nop 0
	v_cndmask_b32_e32 v66, v224, v225, vcc
	v_and_b32_e32 v67, v66, v0
	v_cmp_lt_i32_e32 vcc, s4, v163
	v_cmp_eq_u32_e64 s[6:7], 0, v67
	v_cmp_ne_u32_e64 s[4:5], 0, v67
	s_or_b64 s[6:7], vcc, s[6:7]
	s_and_saveexec_b64 s[10:11], s[6:7]
	s_cbranch_execz .LBB0_458
	s_movk_i32 s6, 0x7f
	v_cmp_gt_i32_e64 s[6:7], s6, v163
	v_cmp_eq_u32_e64 s[8:9], v67, v66
	v_cmp_ne_u32_e32 vcc, v67, v66
	s_or_b64 s[6:7], s[6:7], s[8:9]
	s_and_b64 exec, exec, s[6:7]
	s_cbranch_execz .LBB0_458
	v_add_u32_e32 v70, 0xfffffef8, v169
	v_mov_b32_e32 v66, 0
	v_mov_b32_e32 v68, 0
	v_mov_b32_e32 v69, 0
	s_and_saveexec_b64 s[6:7], s[4:5]
	v_lshl_add_u32 v67, v165, 1, v70
	ds_read_b64 v[68:69], v67
	s_or_b64 exec, exec, s[6:7]
	v_mov_b32_e32 v67, 0
	s_and_saveexec_b64 s[6:7], vcc
	v_lshl_add_u32 v66, v165, 1, v169
	ds_read_b64 v[66:67], v66 offset:264
	s_or_b64 exec, exec, s[6:7]
	s_waitcnt lgkmcnt(0)
	v_lshlrev_b32_e32 v74, 16, v68
	v_and_b32_e32 v75, 0xffff0000, v68
	s_waitcnt vmcnt(5)
	v_pk_mul_f32 v[74:75], v[50:51], v[74:75]
	v_lshlrev_b32_e32 v76, 16, v66
	v_pk_fma_f32 v[74:75], v[42:43], v[130:131], v[74:75]
	v_and_b32_e32 v77, 0xffff0000, v66
	v_pk_fma_f32 v[74:75], v[46:47], v[76:77], v[74:75]
	v_mov_b64_e32 v[72:73], s[2:3]
	s_waitcnt vmcnt(3)
	v_pk_add_f32 v[74:75], v[54:55], v[74:75]
	s_movk_i32 s6, 0x1600
	v_pk_mul_f32 v[76:77], v[74:75], v[74:75]
	v_mad_i64_i32 v[72:73], s[6:7], v0, s6, v[72:73]
	v_fmamk_f32 v0, v76, 0x3dd2d3e7, v209
	v_mul_f32_e64 v0, v0, -v74
	v_exp_f32_e32 v0, v0
	v_mov_b32_e32 v171, v170
	v_pk_mul_f32 v[62:63], v[62:63], v[170:171]
	v_lshlrev_b32_e32 v68, 16, v69
	v_add_f32_e32 v0, 1.0, v0
	v_rcp_f32_e32 v76, v0
	v_fmamk_f32 v0, v77, 0x3dd2d3e7, v209
	v_mul_f32_e64 v0, v0, -v75
	v_exp_f32_e32 v0, v0
	v_and_b32_e32 v69, 0xffff0000, v69
	v_pk_mul_f32 v[64:65], v[64:65], v[170:171]
	v_add_f32_e32 v0, 1.0, v0
	v_rcp_f32_e32 v77, v0
	s_nop 0
	v_pk_mul_f32 v[74:75], v[74:75], v[76:77]
	s_nop 0
	v_pk_mul_f32 v[62:63], v[62:63], v[74:75]
	s_nop 0
	v_cvt_pk_bf16_f32 v240, v62, v63
	v_pk_mul_f32 v[62:63], v[52:53], v[68:69]
	v_lshlrev_b32_e32 v68, 16, v67
	v_pk_fma_f32 v[62:63], v[44:45], v[128:129], v[62:63]
	v_and_b32_e32 v69, 0xffff0000, v67
	v_pk_fma_f32 v[62:63], v[48:49], v[68:69], v[62:63]
	s_nop 0
	v_pk_add_f32 v[62:63], v[56:57], v[62:63]
	s_nop 0
	v_pk_mul_f32 v[68:69], v[62:63], v[62:63]
	s_nop 0
	v_fmamk_f32 v0, v68, 0x3dd2d3e7, v209
	v_mul_f32_e64 v0, v0, -v62
	v_exp_f32_e32 v0, v0
	s_nop 0
	v_add_f32_e32 v0, 1.0, v0
	v_rcp_f32_e32 v68, v0
	v_fmamk_f32 v0, v69, 0x3dd2d3e7, v209
	v_mul_f32_e64 v0, v0, -v63
	v_exp_f32_e32 v0, v0
	s_nop 0
	v_add_f32_e32 v0, 1.0, v0
	v_rcp_f32_e32 v69, v0
	v_lshl_add_u32 v0, v165, 1, v244
	v_pk_mul_f32 v[62:63], v[62:63], v[68:69]
	s_nop 0
	v_pk_mul_f32 v[62:63], v[64:65], v[62:63]
	v_mov_b32_e32 v64, 0
	v_cvt_pk_bf16_f32 v241, v62, v63
	v_lshl_add_u64 v[62:63], v[72:73], 0, v[0:1]
	v_or_b32_e32 v0, 16, v165
	v_mov_b32_e32 v66, 0
	v_mov_b32_e32 v67, 0
	s_and_saveexec_b64 s[6:7], s[4:5]
	v_lshl_add_u32 v65, v0, 1, v70
	ds_read_b64 v[66:67], v65
	s_or_b64 exec, exec, s[6:7]
	v_mov_b32_e32 v65, 0
	s_and_saveexec_b64 s[4:5], vcc
	v_lshl_add_u32 v0, v0, 1, v169
	ds_read_b64 v[64:65], v0 offset:264
	s_or_b64 exec, exec, s[4:5]
	s_waitcnt lgkmcnt(0)
	v_lshlrev_b32_e32 v68, 16, v66
	v_and_b32_e32 v69, 0xffff0000, v66
	v_pk_mul_f32 v[68:69], v[26:27], v[68:69]
	v_lshlrev_b32_e32 v70, 16, v64
	s_waitcnt vmcnt(2)
	v_pk_fma_f32 v[68:69], v[38:39], v[126:127], v[68:69]
	v_and_b32_e32 v71, 0xffff0000, v64
	s_waitcnt vmcnt(1)
	v_pk_fma_f32 v[68:69], v[34:35], v[70:71], v[68:69]
	v_lshlrev_b32_e32 v66, 16, v67
	v_pk_add_f32 v[68:69], v[30:31], v[68:69]
	v_and_b32_e32 v67, 0xffff0000, v67
	v_pk_mul_f32 v[70:71], v[68:69], v[68:69]
	v_pk_mul_f32 v[66:67], v[28:29], v[66:67]
	v_fmamk_f32 v0, v70, 0x3dd2d3e7, v209
	v_mul_f32_e64 v0, v0, -v68
	v_exp_f32_e32 v0, v0
	v_pk_fma_f32 v[66:67], v[40:41], v[124:125], v[66:67]
	v_lshlrev_b32_e32 v64, 16, v65
	v_and_b32_e32 v65, 0xffff0000, v65
	v_add_f32_e32 v0, 1.0, v0
	v_rcp_f32_e32 v70, v0
	v_fmamk_f32 v0, v71, 0x3dd2d3e7, v209
	v_mul_f32_e64 v0, v0, -v69
	v_exp_f32_e32 v0, v0
	v_pk_fma_f32 v[64:65], v[36:37], v[64:65], v[66:67]
	v_pk_mul_f32 v[58:59], v[58:59], v[170:171]
	v_pk_add_f32 v[64:65], v[32:33], v[64:65]
	v_add_f32_e32 v0, 1.0, v0
	v_pk_mul_f32 v[66:67], v[64:65], v[64:65]
	v_rcp_f32_e32 v71, v0
	v_fmamk_f32 v0, v66, 0x3dd2d3e7, v209
	v_mul_f32_e64 v0, v0, -v64
	v_exp_f32_e32 v0, v0
	v_pk_mul_f32 v[68:69], v[68:69], v[70:71]
	v_pk_mul_f32 v[60:61], v[60:61], v[170:171]
	v_pk_mul_f32 v[58:59], v[58:59], v[68:69]
	v_add_f32_e32 v0, 1.0, v0
	v_rcp_f32_e32 v66, v0
	v_fmamk_f32 v0, v67, 0x3dd2d3e7, v209
	v_mul_f32_e64 v0, v0, -v65
	v_exp_f32_e32 v0, v0
	v_cvt_pk_bf16_f32 v242, v58, v59
	v_add_f32_e32 v0, 1.0, v0
	v_rcp_f32_e32 v67, v0
	s_nop 0
	v_pk_mul_f32 v[64:65], v[64:65], v[66:67]
	s_nop 0
	v_pk_mul_f32 v[60:61], v[60:61], v[64:65]
	s_nop 0
	v_cvt_pk_bf16_f32 v243, v60, v61
	s_nop 1
	v_permlane16_swap_b32_e32 v240, v242
	v_permlane16_swap_b32_e32 v241, v243
	global_store_dwordx4 v[62:63], v[240:243], off
; __device__ __forceinline__ float lo2f(unsigned u) { return __uint_as_float(u << 16); }
; __device__ __forceinline__ float hi2f(unsigned u) { return __uint_as_float(u & 0xffff0000u); }
; __device__ __forceinline__ float gelu_f(float x) {
;   const float c2 = 2.f * 0.7978845608028654f * 1.4426950408889634f;
;   float p = __builtin_fmaf(x * x, 0.044715f * c2, c2);
;   float e = __builtin_amdgcn_exp2f(-x * p);
;   return x * __builtin_amdgcn_rcpf(1.f + e);
; template <int MODE>
; __device__ __forceinline__ void gemm_tile(const int ph, const int which, const int pm, const int pn) {
;     ...
;       for (int m = 0; m < 4; ++m) {
;         const int lr = ai * HALF + wr * 64 + m * 16 + fr;
;         const int gr = browC + lr;
;         const int L = gr < 32768 ? 2048 : 4096;
;         const int pos = gr & (L - 1);
;         if ((lr >= 1 || pos == 0) && (lr <= 254 || pos == L - 1)) {
;           const float s = rsv[ai][m];
;           bf16_t* arow = C + (size_t)gr * DFF;
;   #pragma unroll
;         for (int n = 0; n < 2; ++n) {
;             const int c = wc * 32 + n * 16 + fq * 4;
;             uint2 pu = make_uint2(0u, 0u), nu = make_uint2(0u, 0u);
;             if (pos != 0) pu = *(const uint2*)(Gs + (lr - 1) * 264 + c * 2);
;             if (pos != L - 1) nu = *(const uint2*)(Gs + (lr + 1) * 264 + c * 2);
;             f32x4 g = acc[ai][0][m][n], v = acc[ai][1][m][n];
;             float g0 = w0[n].x * lo2f(pu.x) + w1[n].x * (g[0] * s) + w2[n].x * lo2f(nu.x) + bb[n].x;
;             float g1 = w0[n].y * hi2f(pu.x) + w1[n].y * (g[1] * s) + w2[n].y * hi2f(nu.x) + bb[n].y;
;             float g2 = w0[n].z * lo2f(pu.y) + w1[n].z * (g[2] * s) + w2[n].z * lo2f(nu.y) + bb[n].z;
;             float g3 = w0[n].w * hi2f(pu.y) + w1[n].w * (g[3] * s) + w2[n].w * hi2f(nu.y) + bb[n].w;
;             uint2 o;
;             o.x = pack2(gelu_f(g0) * (v[0] * s), gelu_f(g1) * (v[1] * s));
;             o.y = pack2(gelu_f(g2) * (v[2] * s), gelu_f(g3) * (v[3] * s));
;             *(uint2*)(arow + ecol + c) = o;
.LBB0_458:
	s_or_b64 exec, exec, s[10:11]
	v_add_u32_e32 v0, 0x90, v164
	v_cmp_gt_i32_e32 vcc, s36, v0
	s_movk_i32 s4, 0xff70
	s_nop 0
	v_cndmask_b32_e32 v58, v224, v225, vcc
	v_and_b32_e32 v59, v58, v0
	v_cmp_lt_i32_e32 vcc, s4, v163
	v_cmp_eq_u32_e64 s[6:7], 0, v59
	v_cmp_ne_u32_e64 s[4:5], 0, v59
	s_or_b64 s[6:7], vcc, s[6:7]
	s_and_saveexec_b64 s[10:11], s[6:7]
	s_cbranch_execz .LBB0_469
	s_movk_i32 s6, 0x6f
	v_cmp_gt_i32_e64 s[6:7], s6, v163
	v_cmp_eq_u32_e64 s[8:9], v59, v58
	v_cmp_ne_u32_e32 vcc, v59, v58
	s_or_b64 s[6:7], s[6:7], s[8:9]
	s_and_b64 exec, exec, s[6:7]
	s_cbranch_execz .LBB0_469
	v_add_u32_e32 v62, 0xfffffef8, v154
	v_mov_b32_e32 v58, 0
	v_mov_b32_e32 v60, 0
	v_mov_b32_e32 v61, 0
	s_and_saveexec_b64 s[6:7], s[4:5]
	v_lshl_add_u32 v59, v165, 1, v62
	ds_read_b64 v[60:61], v59
	s_or_b64 exec, exec, s[6:7]
	v_mov_b32_e32 v59, 0
	s_and_saveexec_b64 s[6:7], vcc
	v_lshl_add_u32 v58, v165, 1, v154
	ds_read_b64 v[58:59], v58 offset:264
	s_or_b64 exec, exec, s[6:7]
	s_waitcnt lgkmcnt(0)
	v_lshlrev_b32_e32 v66, 16, v60
	v_and_b32_e32 v67, 0xffff0000, v60
	s_waitcnt vmcnt(5)
	v_pk_mul_f32 v[66:67], v[50:51], v[66:67]
	v_lshlrev_b32_e32 v68, 16, v58
	v_pk_fma_f32 v[66:67], v[42:43], v[122:123], v[66:67]
	v_and_b32_e32 v69, 0xffff0000, v58
	v_pk_fma_f32 v[66:67], v[46:47], v[68:69], v[66:67]
	v_mov_b64_e32 v[64:65], s[2:3]
	s_waitcnt vmcnt(3)
	v_pk_add_f32 v[66:67], v[54:55], v[66:67]
	s_movk_i32 s6, 0x1600
	v_pk_mul_f32 v[68:69], v[66:67], v[66:67]
	v_mad_i64_i32 v[64:65], s[6:7], v0, s6, v[64:65]
	v_fmamk_f32 v0, v68, 0x3dd2d3e7, v209
	v_mul_f32_e64 v0, v0, -v66
	v_exp_f32_e32 v0, v0
	v_mov_b32_e32 v169, v168
	v_pk_mul_f32 v[22:23], v[22:23], v[168:169]
	v_lshlrev_b32_e32 v60, 16, v61
	v_add_f32_e32 v0, 1.0, v0
	v_rcp_f32_e32 v68, v0
	v_fmamk_f32 v0, v69, 0x3dd2d3e7, v209
	v_mul_f32_e64 v0, v0, -v67
	v_exp_f32_e32 v0, v0
	v_and_b32_e32 v61, 0xffff0000, v61
	v_pk_mul_f32 v[24:25], v[24:25], v[168:169]
	v_add_f32_e32 v0, 1.0, v0
	v_rcp_f32_e32 v69, v0
	s_nop 0
	v_pk_mul_f32 v[66:67], v[66:67], v[68:69]
	s_nop 0
	v_pk_mul_f32 v[22:23], v[22:23], v[66:67]
	s_nop 0
	v_cvt_pk_bf16_f32 v240, v22, v23
	v_pk_mul_f32 v[22:23], v[52:53], v[60:61]
	v_lshlrev_b32_e32 v60, 16, v59
	v_pk_fma_f32 v[22:23], v[44:45], v[120:121], v[22:23]
	v_and_b32_e32 v61, 0xffff0000, v59
	v_pk_fma_f32 v[22:23], v[48:49], v[60:61], v[22:23]
	s_nop 0
	v_pk_add_f32 v[22:23], v[56:57], v[22:23]
	s_nop 0
	v_pk_mul_f32 v[60:61], v[22:23], v[22:23]
	s_nop 0
	v_fmamk_f32 v0, v60, 0x3dd2d3e7, v209
	v_mul_f32_e64 v0, v0, -v22
	v_exp_f32_e32 v0, v0
	s_nop 0
	v_add_f32_e32 v0, 1.0, v0
	v_rcp_f32_e32 v60, v0
	v_fmamk_f32 v0, v61, 0x3dd2d3e7, v209
	v_mul_f32_e64 v0, v0, -v23
	v_exp_f32_e32 v0, v0
	s_nop 0
	v_add_f32_e32 v0, 1.0, v0
	v_rcp_f32_e32 v61, v0
	v_lshl_add_u32 v0, v165, 1, v244
	v_pk_mul_f32 v[22:23], v[22:23], v[60:61]
	s_nop 0
	v_pk_mul_f32 v[22:23], v[24:25], v[22:23]
	v_mov_b32_e32 v24, 0
	v_cvt_pk_bf16_f32 v241, v22, v23
	v_lshl_add_u64 v[22:23], v[64:65], 0, v[0:1]
	v_or_b32_e32 v0, 16, v165
	v_mov_b32_e32 v58, 0
	v_mov_b32_e32 v59, 0
	s_and_saveexec_b64 s[6:7], s[4:5]
	v_lshl_add_u32 v25, v0, 1, v62
	ds_read_b64 v[58:59], v25
	s_or_b64 exec, exec, s[6:7]
	v_mov_b32_e32 v25, 0
	s_and_saveexec_b64 s[4:5], vcc
	v_lshl_add_u32 v0, v0, 1, v154
	ds_read_b64 v[24:25], v0 offset:264
	s_or_b64 exec, exec, s[4:5]
	s_waitcnt lgkmcnt(0)
	v_lshlrev_b32_e32 v60, 16, v58
	v_and_b32_e32 v61, 0xffff0000, v58
	v_pk_mul_f32 v[60:61], v[26:27], v[60:61]
	v_lshlrev_b32_e32 v62, 16, v24
	s_waitcnt vmcnt(2)
	v_pk_fma_f32 v[60:61], v[38:39], v[118:119], v[60:61]
	v_and_b32_e32 v63, 0xffff0000, v24
	s_waitcnt vmcnt(1)
	v_pk_fma_f32 v[60:61], v[34:35], v[62:63], v[60:61]
	v_lshlrev_b32_e32 v58, 16, v59
	v_pk_add_f32 v[60:61], v[30:31], v[60:61]
	v_and_b32_e32 v59, 0xffff0000, v59
	v_pk_mul_f32 v[62:63], v[60:61], v[60:61]
	v_pk_mul_f32 v[58:59], v[28:29], v[58:59]
	v_fmamk_f32 v0, v62, 0x3dd2d3e7, v209
	v_mul_f32_e64 v0, v0, -v60
	v_exp_f32_e32 v0, v0
	v_pk_fma_f32 v[58:59], v[40:41], v[116:117], v[58:59]
	v_lshlrev_b32_e32 v24, 16, v25
	v_and_b32_e32 v25, 0xffff0000, v25
	v_add_f32_e32 v0, 1.0, v0
	v_rcp_f32_e32 v62, v0
	v_fmamk_f32 v0, v63, 0x3dd2d3e7, v209
	v_mul_f32_e64 v0, v0, -v61
	v_exp_f32_e32 v0, v0
	v_pk_fma_f32 v[24:25], v[36:37], v[24:25], v[58:59]
	v_pk_mul_f32 v[18:19], v[18:19], v[168:169]
	v_pk_add_f32 v[24:25], v[32:33], v[24:25]
	v_add_f32_e32 v0, 1.0, v0
	v_pk_mul_f32 v[58:59], v[24:25], v[24:25]
	v_rcp_f32_e32 v63, v0
	v_fmamk_f32 v0, v58, 0x3dd2d3e7, v209
	v_mul_f32_e64 v0, v0, -v24
	v_exp_f32_e32 v0, v0
	v_pk_mul_f32 v[60:61], v[60:61], v[62:63]
	v_pk_mul_f32 v[20:21], v[20:21], v[168:169]
	v_pk_mul_f32 v[18:19], v[18:19], v[60:61]
	v_add_f32_e32 v0, 1.0, v0
	v_rcp_f32_e32 v58, v0
	v_fmamk_f32 v0, v59, 0x3dd2d3e7, v209
	v_mul_f32_e64 v0, v0, -v25
	v_exp_f32_e32 v0, v0
	v_cvt_pk_bf16_f32 v242, v18, v19
	v_add_f32_e32 v0, 1.0, v0
	v_rcp_f32_e32 v59, v0
	s_nop 0
	v_pk_mul_f32 v[24:25], v[24:25], v[58:59]
	s_nop 0
	v_pk_mul_f32 v[20:21], v[20:21], v[24:25]
	s_nop 0
	v_cvt_pk_bf16_f32 v243, v20, v21
	s_nop 1
	v_permlane16_swap_b32_e32 v240, v242
	v_permlane16_swap_b32_e32 v241, v243
	global_store_dwordx4 v[22:23], v[240:243], off
; __device__ __forceinline__ float lo2f(unsigned u) { return __uint_as_float(u << 16); }
; __device__ __forceinline__ float hi2f(unsigned u) { return __uint_as_float(u & 0xffff0000u); }
; __device__ __forceinline__ float gelu_f(float x) {
;   const float c2 = 2.f * 0.7978845608028654f * 1.4426950408889634f;
;   float p = __builtin_fmaf(x * x, 0.044715f * c2, c2);
;   float e = __builtin_amdgcn_exp2f(-x * p);
;   return x * __builtin_amdgcn_rcpf(1.f + e);
; template <int MODE>
; __device__ __forceinline__ void gemm_tile(const int ph, const int which, const int pm, const int pn) {
;     ...
;       for (int m = 0; m < 4; ++m) {
;         const int lr = ai * HALF + wr * 64 + m * 16 + fr;
;         const int gr = browC + lr;
;         const int L = gr < 32768 ? 2048 : 4096;
;         const int pos = gr & (L - 1);
;         if ((lr >= 1 || pos == 0) && (lr <= 254 || pos == L - 1)) {
;           const float s = rsv[ai][m];
;           bf16_t* arow = C + (size_t)gr * DFF;
;   #pragma unroll
;         for (int n = 0; n < 2; ++n) {
;             const int c = wc * 32 + n * 16 + fq * 4;
;             uint2 pu = make_uint2(0u, 0u), nu = make_uint2(0u, 0u);
;             if (pos != 0) pu = *(const uint2*)(Gs + (lr - 1) * 264 + c * 2);
;             if (pos != L - 1) nu = *(const uint2*)(Gs + (lr + 1) * 264 + c * 2);
;             f32x4 g = acc[ai][0][m][n], v = acc[ai][1][m][n];
;             float g0 = w0[n].x * lo2f(pu.x) + w1[n].x * (g[0] * s) + w2[n].x * lo2f(nu.x) + bb[n].x;
;             float g1 = w0[n].y * hi2f(pu.x) + w1[n].y * (g[1] * s) + w2[n].y * hi2f(nu.x) + bb[n].y;
;             float g2 = w0[n].z * lo2f(pu.y) + w1[n].z * (g[2] * s) + w2[n].z * lo2f(nu.y) + bb[n].z;
;             float g3 = w0[n].w * hi2f(pu.y) + w1[n].w * (g[3] * s) + w2[n].w * hi2f(nu.y) + bb[n].w;
;             uint2 o;
;             o.x = pack2(gelu_f(g0) * (v[0] * s), gelu_f(g1) * (v[1] * s));
;             o.y = pack2(gelu_f(g2) * (v[2] * s), gelu_f(g3) * (v[3] * s));
;             *(uint2*)(arow + ecol + c) = o;
.LBB0_469:
	s_or_b64 exec, exec, s[10:11]
	v_add_u32_e32 v0, 0xa0, v164
	v_cmp_gt_i32_e32 vcc, s36, v0
	s_movk_i32 s4, 0xff60
	s_nop 0
	v_cndmask_b32_e32 v18, v224, v225, vcc
	v_and_b32_e32 v19, v18, v0
	v_cmp_lt_i32_e32 vcc, s4, v163
	v_cmp_eq_u32_e64 s[6:7], 0, v19
	v_cmp_ne_u32_e64 s[4:5], 0, v19
	s_or_b64 s[6:7], vcc, s[6:7]
	s_and_saveexec_b64 s[10:11], s[6:7]
	s_cbranch_execz .LBB0_480
	s_movk_i32 s6, 0x5f
	v_cmp_gt_i32_e64 s[6:7], s6, v163
	v_cmp_eq_u32_e64 s[8:9], v19, v18
	v_cmp_ne_u32_e32 vcc, v19, v18
	s_or_b64 s[6:7], s[6:7], s[8:9]
	s_and_b64 exec, exec, s[6:7]
	s_cbranch_execz .LBB0_480
	v_add_u32_e32 v22, 0xfffffef8, v146
	v_mov_b32_e32 v18, 0
	v_mov_b32_e32 v20, 0
	v_mov_b32_e32 v21, 0
	s_and_saveexec_b64 s[6:7], s[4:5]
	v_lshl_add_u32 v19, v165, 1, v22
	ds_read_b64 v[20:21], v19
	s_or_b64 exec, exec, s[6:7]
	v_mov_b32_e32 v19, 0
	s_and_saveexec_b64 s[6:7], vcc
	v_lshl_add_u32 v18, v165, 1, v146
	ds_read_b64 v[18:19], v18 offset:264
	s_or_b64 exec, exec, s[6:7]
	s_waitcnt lgkmcnt(0)
	v_lshlrev_b32_e32 v58, 16, v20
	v_and_b32_e32 v59, 0xffff0000, v20
	s_waitcnt vmcnt(5)
	v_pk_mul_f32 v[58:59], v[50:51], v[58:59]
	v_lshlrev_b32_e32 v60, 16, v18
	v_pk_fma_f32 v[58:59], v[42:43], v[114:115], v[58:59]
	v_and_b32_e32 v61, 0xffff0000, v18
	v_pk_fma_f32 v[58:59], v[46:47], v[60:61], v[58:59]
	v_mov_b64_e32 v[24:25], s[2:3]
	s_waitcnt vmcnt(3)
	v_pk_add_f32 v[58:59], v[54:55], v[58:59]
	s_movk_i32 s6, 0x1600
	v_pk_mul_f32 v[60:61], v[58:59], v[58:59]
	v_mad_i64_i32 v[24:25], s[6:7], v0, s6, v[24:25]
	v_fmamk_f32 v0, v60, 0x3dd2d3e7, v209
	v_mul_f32_e64 v0, v0, -v58
	v_exp_f32_e32 v0, v0
	v_mov_b32_e32 v167, v166
	v_pk_mul_f32 v[14:15], v[14:15], v[166:167]
	v_lshlrev_b32_e32 v20, 16, v21
	v_add_f32_e32 v0, 1.0, v0
	v_rcp_f32_e32 v60, v0
	v_fmamk_f32 v0, v61, 0x3dd2d3e7, v209
	v_mul_f32_e64 v0, v0, -v59
	v_exp_f32_e32 v0, v0
	v_and_b32_e32 v21, 0xffff0000, v21
	v_pk_mul_f32 v[16:17], v[16:17], v[166:167]
	v_add_f32_e32 v0, 1.0, v0
	v_rcp_f32_e32 v61, v0
	s_nop 0
	v_pk_mul_f32 v[58:59], v[58:59], v[60:61]
	s_nop 0
	v_pk_mul_f32 v[14:15], v[14:15], v[58:59]
	s_nop 0
	v_cvt_pk_bf16_f32 v240, v14, v15
	v_pk_mul_f32 v[14:15], v[52:53], v[20:21]
	v_lshlrev_b32_e32 v20, 16, v19
	v_pk_fma_f32 v[14:15], v[44:45], v[112:113], v[14:15]
	v_and_b32_e32 v21, 0xffff0000, v19
	v_pk_fma_f32 v[14:15], v[48:49], v[20:21], v[14:15]
	s_nop 0
	v_pk_add_f32 v[14:15], v[56:57], v[14:15]
	s_nop 0
	v_pk_mul_f32 v[20:21], v[14:15], v[14:15]
	s_nop 0
	v_fmamk_f32 v0, v20, 0x3dd2d3e7, v209
	v_mul_f32_e64 v0, v0, -v14
	v_exp_f32_e32 v0, v0
	s_nop 0
	v_add_f32_e32 v0, 1.0, v0
	v_rcp_f32_e32 v20, v0
	v_fmamk_f32 v0, v21, 0x3dd2d3e7, v209
	v_mul_f32_e64 v0, v0, -v15
	v_exp_f32_e32 v0, v0
	s_nop 0
	v_add_f32_e32 v0, 1.0, v0
	v_rcp_f32_e32 v21, v0
	v_lshl_add_u32 v0, v165, 1, v244
	v_pk_mul_f32 v[14:15], v[14:15], v[20:21]
	s_nop 0
	v_pk_mul_f32 v[14:15], v[16:17], v[14:15]
	v_mov_b32_e32 v16, 0
	v_cvt_pk_bf16_f32 v241, v14, v15
	v_lshl_add_u64 v[14:15], v[24:25], 0, v[0:1]
	v_or_b32_e32 v0, 16, v165
	v_mov_b32_e32 v18, 0
	v_mov_b32_e32 v19, 0
	s_and_saveexec_b64 s[6:7], s[4:5]
	v_lshl_add_u32 v17, v0, 1, v22
	ds_read_b64 v[18:19], v17
	s_or_b64 exec, exec, s[6:7]
	v_mov_b32_e32 v17, 0
	s_and_saveexec_b64 s[4:5], vcc
	v_lshl_add_u32 v0, v0, 1, v146
	ds_read_b64 v[16:17], v0 offset:264
	s_or_b64 exec, exec, s[4:5]
	s_waitcnt lgkmcnt(0)
	v_lshlrev_b32_e32 v20, 16, v18
	v_and_b32_e32 v21, 0xffff0000, v18
	v_pk_mul_f32 v[20:21], v[26:27], v[20:21]
	v_lshlrev_b32_e32 v22, 16, v16
	s_waitcnt vmcnt(2)
	v_pk_fma_f32 v[20:21], v[38:39], v[110:111], v[20:21]
	v_and_b32_e32 v23, 0xffff0000, v16
	s_waitcnt vmcnt(1)
	v_pk_fma_f32 v[20:21], v[34:35], v[22:23], v[20:21]
	v_lshlrev_b32_e32 v18, 16, v19
	v_pk_add_f32 v[20:21], v[30:31], v[20:21]
	v_and_b32_e32 v19, 0xffff0000, v19
	v_pk_mul_f32 v[22:23], v[20:21], v[20:21]
	v_pk_mul_f32 v[18:19], v[28:29], v[18:19]
	v_fmamk_f32 v0, v22, 0x3dd2d3e7, v209
	v_mul_f32_e64 v0, v0, -v20
	v_exp_f32_e32 v0, v0
	v_pk_fma_f32 v[18:19], v[40:41], v[108:109], v[18:19]
	v_lshlrev_b32_e32 v16, 16, v17
	v_and_b32_e32 v17, 0xffff0000, v17
	v_add_f32_e32 v0, 1.0, v0
	v_rcp_f32_e32 v22, v0
	v_fmamk_f32 v0, v23, 0x3dd2d3e7, v209
	v_mul_f32_e64 v0, v0, -v21
	v_exp_f32_e32 v0, v0
	v_pk_fma_f32 v[16:17], v[36:37], v[16:17], v[18:19]
	v_pk_mul_f32 v[10:11], v[10:11], v[166:167]
	v_pk_add_f32 v[16:17], v[32:33], v[16:17]
	v_add_f32_e32 v0, 1.0, v0
	v_pk_mul_f32 v[18:19], v[16:17], v[16:17]
	v_rcp_f32_e32 v23, v0
	v_fmamk_f32 v0, v18, 0x3dd2d3e7, v209
	v_mul_f32_e64 v0, v0, -v16
	v_exp_f32_e32 v0, v0
	v_pk_mul_f32 v[20:21], v[20:21], v[22:23]
	v_pk_mul_f32 v[12:13], v[12:13], v[166:167]
	v_pk_mul_f32 v[10:11], v[10:11], v[20:21]
	v_add_f32_e32 v0, 1.0, v0
	v_rcp_f32_e32 v18, v0
	v_fmamk_f32 v0, v19, 0x3dd2d3e7, v209
	v_mul_f32_e64 v0, v0, -v17
	v_exp_f32_e32 v0, v0
	v_cvt_pk_bf16_f32 v242, v10, v11
	v_add_f32_e32 v0, 1.0, v0
	v_rcp_f32_e32 v19, v0
	s_nop 0
	v_pk_mul_f32 v[16:17], v[16:17], v[18:19]
	s_nop 0
	v_pk_mul_f32 v[12:13], v[12:13], v[16:17]
	s_nop 0
	v_cvt_pk_bf16_f32 v243, v12, v13
	s_nop 1
	v_permlane16_swap_b32_e32 v240, v242
	v_permlane16_swap_b32_e32 v241, v243
	global_store_dwordx4 v[14:15], v[240:243], off
; __device__ __forceinline__ float lo2f(unsigned u) { return __uint_as_float(u << 16); }
; __device__ __forceinline__ float hi2f(unsigned u) { return __uint_as_float(u & 0xffff0000u); }
; __device__ __forceinline__ float gelu_f(float x) {
;   const float c2 = 2.f * 0.7978845608028654f * 1.4426950408889634f;
;   float p = __builtin_fmaf(x * x, 0.044715f * c2, c2);
;   float e = __builtin_amdgcn_exp2f(-x * p);
;   return x * __builtin_amdgcn_rcpf(1.f + e);
; template <int MODE>
; __device__ __forceinline__ void gemm_tile(const int ph, const int which, const int pm, const int pn) {
;     ...
;       for (int m = 0; m < 4; ++m) {
;         const int lr = ai * HALF + wr * 64 + m * 16 + fr;
;         const int gr = browC + lr;
;         const int L = gr < 32768 ? 2048 : 4096;
;         const int pos = gr & (L - 1);
;         if ((lr >= 1 || pos == 0) && (lr <= 254 || pos == L - 1)) {
;           const float s = rsv[ai][m];
;           bf16_t* arow = C + (size_t)gr * DFF;
;   #pragma unroll
;         for (int n = 0; n < 2; ++n) {
;             const int c = wc * 32 + n * 16 + fq * 4;
;             uint2 pu = make_uint2(0u, 0u), nu = make_uint2(0u, 0u);
;             if (pos != 0) pu = *(const uint2*)(Gs + (lr - 1) * 264 + c * 2);
;             if (pos != L - 1) nu = *(const uint2*)(Gs + (lr + 1) * 264 + c * 2);
;             f32x4 g = acc[ai][0][m][n], v = acc[ai][1][m][n];
;             float g0 = w0[n].x * lo2f(pu.x) + w1[n].x * (g[0] * s) + w2[n].x * lo2f(nu.x) + bb[n].x;
;             float g1 = w0[n].y * hi2f(pu.x) + w1[n].y * (g[1] * s) + w2[n].y * hi2f(nu.x) + bb[n].y;
;             float g2 = w0[n].z * lo2f(pu.y) + w1[n].z * (g[2] * s) + w2[n].z * lo2f(nu.y) + bb[n].z;
;             float g3 = w0[n].w * hi2f(pu.y) + w1[n].w * (g[3] * s) + w2[n].w * hi2f(nu.y) + bb[n].w;
;             uint2 o;
;             o.x = pack2(gelu_f(g0) * (v[0] * s), gelu_f(g1) * (v[1] * s));
;             o.y = pack2(gelu_f(g2) * (v[2] * s), gelu_f(g3) * (v[3] * s));
;             *(uint2*)(arow + ecol + c) = o;
.LBB0_480:
	s_or_b64 exec, exec, s[10:11]
	v_add_u32_e32 v0, 0xb0, v164
	v_cmp_gt_i32_e32 vcc, s36, v0
	s_movk_i32 s4, 0xff50
	s_nop 0
	v_cndmask_b32_e32 v10, v224, v225, vcc
	v_and_b32_e32 v11, v10, v0
	v_cmp_lt_i32_e32 vcc, s4, v163
	v_cmp_eq_u32_e64 s[6:7], 0, v11
	v_cmp_ne_u32_e64 s[4:5], 0, v11
	s_or_b64 s[6:7], vcc, s[6:7]
	s_and_saveexec_b64 s[10:11], s[6:7]
	s_cbranch_execz .LBB0_491
	s_movk_i32 s6, 0x4f
	v_cmp_gt_i32_e64 s[6:7], s6, v163
	v_cmp_eq_u32_e64 s[8:9], v11, v10
	v_cmp_ne_u32_e32 vcc, v11, v10
	s_or_b64 s[6:7], s[6:7], s[8:9]
	s_and_b64 exec, exec, s[6:7]
	s_cbranch_execz .LBB0_491
	v_add_u32_e32 v14, 0xfffffef8, v138
	v_mov_b32_e32 v10, 0
	v_mov_b32_e32 v12, 0
	v_mov_b32_e32 v13, 0
	s_and_saveexec_b64 s[6:7], s[4:5]
	v_lshl_add_u32 v11, v165, 1, v14
	ds_read_b64 v[12:13], v11
	s_or_b64 exec, exec, s[6:7]
	v_mov_b32_e32 v11, 0
	s_and_saveexec_b64 s[6:7], vcc
	v_lshl_add_u32 v10, v165, 1, v138
	ds_read_b64 v[10:11], v10 offset:264
	s_or_b64 exec, exec, s[6:7]
	s_waitcnt lgkmcnt(0)
	v_lshlrev_b32_e32 v18, 16, v12
	v_and_b32_e32 v19, 0xffff0000, v12
	s_waitcnt vmcnt(5)
	v_pk_mul_f32 v[18:19], v[50:51], v[18:19]
	v_lshlrev_b32_e32 v20, 16, v10
	v_pk_fma_f32 v[18:19], v[42:43], v[106:107], v[18:19]
	v_and_b32_e32 v21, 0xffff0000, v10
	v_pk_fma_f32 v[18:19], v[46:47], v[20:21], v[18:19]
	v_mov_b64_e32 v[16:17], s[2:3]
	s_waitcnt vmcnt(3)
	v_pk_add_f32 v[18:19], v[54:55], v[18:19]
	s_movk_i32 s2, 0x1600
	v_pk_mul_f32 v[20:21], v[18:19], v[18:19]
	v_mad_i64_i32 v[16:17], s[2:3], v0, s2, v[16:17]
	v_fmamk_f32 v0, v20, 0x3dd2d3e7, v209
	v_mul_f32_e64 v0, v0, -v18
	v_exp_f32_e32 v0, v0
	v_mov_b32_e32 v163, v162
	v_pk_mul_f32 v[6:7], v[6:7], v[162:163]
	v_lshlrev_b32_e32 v12, 16, v13
	v_add_f32_e32 v0, 1.0, v0
	v_rcp_f32_e32 v20, v0
	v_fmamk_f32 v0, v21, 0x3dd2d3e7, v209
	v_mul_f32_e64 v0, v0, -v19
	v_exp_f32_e32 v0, v0
	v_and_b32_e32 v13, 0xffff0000, v13
	v_pk_mul_f32 v[8:9], v[8:9], v[162:163]
	v_add_f32_e32 v0, 1.0, v0
	v_rcp_f32_e32 v21, v0
	s_nop 0
	v_pk_mul_f32 v[18:19], v[18:19], v[20:21]
	s_nop 0
	v_pk_mul_f32 v[6:7], v[6:7], v[18:19]
	s_nop 0
	v_cvt_pk_bf16_f32 v240, v6, v7
	v_pk_mul_f32 v[6:7], v[52:53], v[12:13]
	v_lshlrev_b32_e32 v12, 16, v11
	v_pk_fma_f32 v[6:7], v[44:45], v[104:105], v[6:7]
	v_and_b32_e32 v13, 0xffff0000, v11
	v_pk_fma_f32 v[6:7], v[48:49], v[12:13], v[6:7]
	s_nop 0
	v_pk_add_f32 v[6:7], v[56:57], v[6:7]
	s_nop 0
	v_pk_mul_f32 v[12:13], v[6:7], v[6:7]
	s_nop 0
	v_fmamk_f32 v0, v12, 0x3dd2d3e7, v209
	v_mul_f32_e64 v0, v0, -v6
	v_exp_f32_e32 v0, v0
	s_nop 0
	v_add_f32_e32 v0, 1.0, v0
	v_rcp_f32_e32 v12, v0
	v_fmamk_f32 v0, v13, 0x3dd2d3e7, v209
	v_mul_f32_e64 v0, v0, -v7
	v_exp_f32_e32 v0, v0
	s_nop 0
	v_add_f32_e32 v0, 1.0, v0
	v_rcp_f32_e32 v13, v0
	v_lshl_add_u32 v0, v165, 1, v244
	v_pk_mul_f32 v[6:7], v[6:7], v[12:13]
	s_nop 0
	v_pk_mul_f32 v[6:7], v[8:9], v[6:7]
	v_mov_b32_e32 v8, 0
	v_cvt_pk_bf16_f32 v241, v6, v7
	v_lshl_add_u64 v[6:7], v[16:17], 0, v[0:1]
	v_or_b32_e32 v0, 16, v165
	v_mov_b32_e32 v10, 0
	v_mov_b32_e32 v11, 0
	s_and_saveexec_b64 s[2:3], s[4:5]
	v_lshl_add_u32 v9, v0, 1, v14
	ds_read_b64 v[10:11], v9
	s_or_b64 exec, exec, s[2:3]
	v_mov_b32_e32 v9, 0
	s_and_saveexec_b64 s[2:3], vcc
	v_lshl_add_u32 v0, v0, 1, v138
	ds_read_b64 v[8:9], v0 offset:264
	s_or_b64 exec, exec, s[2:3]
	s_waitcnt lgkmcnt(0)
	v_lshlrev_b32_e32 v12, 16, v10
	v_and_b32_e32 v13, 0xffff0000, v10
	v_pk_mul_f32 v[12:13], v[26:27], v[12:13]
	v_lshlrev_b32_e32 v14, 16, v8
	s_waitcnt vmcnt(2)
	v_pk_fma_f32 v[12:13], v[38:39], v[102:103], v[12:13]
	v_and_b32_e32 v15, 0xffff0000, v8
	s_waitcnt vmcnt(1)
	v_pk_fma_f32 v[12:13], v[34:35], v[14:15], v[12:13]
	v_lshlrev_b32_e32 v10, 16, v11
	v_pk_add_f32 v[12:13], v[30:31], v[12:13]
	v_and_b32_e32 v11, 0xffff0000, v11
	v_pk_mul_f32 v[14:15], v[12:13], v[12:13]
	v_pk_mul_f32 v[10:11], v[28:29], v[10:11]
	v_fmamk_f32 v0, v14, 0x3dd2d3e7, v209
	v_mul_f32_e64 v0, v0, -v12
	v_exp_f32_e32 v0, v0
	v_pk_fma_f32 v[10:11], v[40:41], v[98:99], v[10:11]
	v_lshlrev_b32_e32 v8, 16, v9
	v_and_b32_e32 v9, 0xffff0000, v9
	v_add_f32_e32 v0, 1.0, v0
	v_rcp_f32_e32 v14, v0
	v_fmamk_f32 v0, v15, 0x3dd2d3e7, v209
	v_mul_f32_e64 v0, v0, -v13
	v_exp_f32_e32 v0, v0
	v_pk_fma_f32 v[8:9], v[36:37], v[8:9], v[10:11]
	v_pk_mul_f32 v[2:3], v[2:3], v[162:163]
	v_pk_add_f32 v[8:9], v[32:33], v[8:9]
	v_add_f32_e32 v0, 1.0, v0
	v_pk_mul_f32 v[10:11], v[8:9], v[8:9]
	v_rcp_f32_e32 v15, v0
	v_fmamk_f32 v0, v10, 0x3dd2d3e7, v209
	v_mul_f32_e64 v0, v0, -v8
	v_exp_f32_e32 v0, v0
	v_pk_mul_f32 v[12:13], v[12:13], v[14:15]
	v_pk_mul_f32 v[4:5], v[4:5], v[162:163]
	v_pk_mul_f32 v[2:3], v[2:3], v[12:13]
	v_add_f32_e32 v0, 1.0, v0
	v_rcp_f32_e32 v10, v0
	v_fmamk_f32 v0, v11, 0x3dd2d3e7, v209
	v_mul_f32_e64 v0, v0, -v9
	v_exp_f32_e32 v0, v0
	v_cvt_pk_bf16_f32 v242, v2, v3
	v_add_f32_e32 v0, 1.0, v0
	v_rcp_f32_e32 v11, v0
	s_nop 0
	v_pk_mul_f32 v[8:9], v[8:9], v[10:11]
	s_nop 0
	v_pk_mul_f32 v[4:5], v[4:5], v[8:9]
	s_nop 0
	v_cvt_pk_bf16_f32 v243, v4, v5
	s_nop 1
	v_permlane16_swap_b32_e32 v240, v242
	v_permlane16_swap_b32_e32 v241, v243
	global_store_dwordx4 v[6:7], v[240:243], off
